# previous + s_setprio 1 on the follower-half (waves 4-7) k-loop path of gemm_in and gemm_f1
# baseline (speedup 1.0000x reference)
; DEVI int otid() { int t = threadIdx.x; asm volatile("" : "+v"(t)); return t; }
; template <int MI, int NC>
; DEVI void gemm_kloop(f32x16 (&acc)[2 * NC][MI], const u16* __restrict__ A, long lda, const u16* __restrict__ Bt, long ldb, int K, char* lds) {
;   const int tid = otid(), wid = tid >> 6, lane = tid & 63, r32 = lane & 31, hi = lane >> 5;
;   const int wm = wid & 3, wn = wid >> 2;
;   constexpr int ABUF = 32768, BBUF = 16384 * NC;
;   char* As = lds; char* Bs = lds + 65536;
;   const int ch = tid & 7, rw = tid >> 3;
;   const int swz = ((ch ^ ((rw >> 1) & 7)) << 4);
;   u32x4 ra[2 * MI], rb[2 * NC];
;   const u16* Ap = A + (long)rw * lda + ch * 8;
;   const u16* Bp = Bt + (long)rw * ldb + ch * 8;
;     ...
; #pragma unroll
;   for (int i = 0; i < 2 * NC; ++i)
; #pragma unroll
;     for (int j = 0; j < MI; ++j)
; #pragma unroll
;       for (int r = 0; r < 16; ++r) acc[i][j][r] = 0.f;
;   const int KT = K >> 6;
;   const int grp = __builtin_amdgcn_readfirstlane(wid) >> 2;
;   const int rowa0 = wn * (64 * NC) + r32, rowb0 = wm * (32 * MI) + r32;
;   const int sa = (rowa0 >> 1) & 7, sb = (rowb0 >> 1) & 7;
.LBB0_135:
	s_and_b64 vcc, exec, s[8:9]
	s_cbranch_vccz .LBB0_139
	s_setprio 1
	s_sub_i32 s3, s39, s40
	s_sub_i32 s3, s3, s27
	s_lshl_b32 s6, s3, 8
	s_ashr_i32 s7, s6, 31
	s_lshl_b64 s[6:7], s[6:7], 11
	s_nop 4
	v_lshl_add_u64 v[0:1], v[200:201], 0, s[6:7]
	v_lshl_add_u64 v[0:1], v[0:1], 0, v[192:193]
	v_lshl_add_u64 v[160:161], s[16:17], 0, v[0:1]
	v_lshl_add_u64 v[0:1], v[202:203], 0, v[192:193]
	v_lshl_add_u64 v[162:163], s[90:91], 0, v[0:1]
	v_mov_b32_e32 v0, 0
	s_mov_b64 s[6:7], 0
	s_mov_b32 s3, 0x8000
	v_mov_b32_e32 v1, v0
	v_mov_b32_e32 v2, v0
	v_mov_b32_e32 v3, v0
	v_mov_b32_e32 v4, v0
	v_mov_b32_e32 v5, v0
	v_mov_b32_e32 v6, v0
	v_mov_b32_e32 v7, v0
	v_mov_b32_e32 v8, v0
	v_mov_b32_e32 v9, v0
	v_mov_b32_e32 v10, v0
	v_mov_b32_e32 v11, v0
	v_mov_b32_e32 v12, v0
	v_mov_b32_e32 v13, v0
	v_mov_b32_e32 v14, v0
	v_mov_b32_e32 v15, v0
	v_mov_b32_e32 v32, v0
	v_mov_b32_e32 v33, v0
	v_mov_b32_e32 v34, v0
	v_mov_b32_e32 v35, v0
	v_mov_b32_e32 v36, v0
	v_mov_b32_e32 v37, v0
	v_mov_b32_e32 v38, v0
	v_mov_b32_e32 v39, v0
	v_mov_b32_e32 v40, v0
	v_mov_b32_e32 v41, v0
	v_mov_b32_e32 v42, v0
	v_mov_b32_e32 v43, v0
	v_mov_b32_e32 v44, v0
	v_mov_b32_e32 v45, v0
	v_mov_b32_e32 v46, v0
	v_mov_b32_e32 v47, v0
	v_mov_b32_e32 v16, v0
	v_mov_b32_e32 v17, v0
	v_mov_b32_e32 v18, v0
	v_mov_b32_e32 v19, v0
	v_mov_b32_e32 v20, v0
	v_mov_b32_e32 v21, v0
	v_mov_b32_e32 v22, v0
	v_mov_b32_e32 v23, v0
	v_mov_b32_e32 v24, v0
	v_mov_b32_e32 v25, v0
	v_mov_b32_e32 v26, v0
	v_mov_b32_e32 v27, v0
	v_mov_b32_e32 v28, v0
	v_mov_b32_e32 v29, v0
	v_mov_b32_e32 v30, v0
	v_mov_b32_e32 v31, v0
	v_mov_b32_e32 v48, v0
	v_mov_b32_e32 v49, v0
	v_mov_b32_e32 v50, v0
	v_mov_b32_e32 v51, v0
	v_mov_b32_e32 v52, v0
	v_mov_b32_e32 v53, v0
	v_mov_b32_e32 v54, v0
	v_mov_b32_e32 v55, v0
	v_mov_b32_e32 v56, v0
	v_mov_b32_e32 v57, v0
	v_mov_b32_e32 v58, v0
	v_mov_b32_e32 v59, v0
	v_mov_b32_e32 v60, v0
	v_mov_b32_e32 v61, v0
	v_mov_b32_e32 v62, v0
	v_mov_b32_e32 v63, v0
	v_mov_b32_e32 v64, v0
	v_mov_b32_e32 v65, v0
	v_mov_b32_e32 v66, v0
	v_mov_b32_e32 v67, v0
	v_mov_b32_e32 v68, v0
	v_mov_b32_e32 v69, v0
	v_mov_b32_e32 v70, v0
	v_mov_b32_e32 v71, v0
	v_mov_b32_e32 v72, v0
	v_mov_b32_e32 v73, v0
	v_mov_b32_e32 v74, v0
	v_mov_b32_e32 v75, v0
	v_mov_b32_e32 v76, v0
	v_mov_b32_e32 v77, v0
	v_mov_b32_e32 v78, v0
	v_mov_b32_e32 v79, v0
	v_mov_b32_e32 v96, v0
	v_mov_b32_e32 v97, v0
	v_mov_b32_e32 v98, v0
	v_mov_b32_e32 v99, v0
	v_mov_b32_e32 v100, v0
	v_mov_b32_e32 v101, v0
	v_mov_b32_e32 v102, v0
	v_mov_b32_e32 v103, v0
	v_mov_b32_e32 v104, v0
	v_mov_b32_e32 v105, v0
	v_mov_b32_e32 v106, v0
	v_mov_b32_e32 v107, v0
	v_mov_b32_e32 v108, v0
	v_mov_b32_e32 v109, v0
	v_mov_b32_e32 v110, v0
	v_mov_b32_e32 v111, v0
	v_mov_b32_e32 v80, v0
	v_mov_b32_e32 v81, v0
	v_mov_b32_e32 v82, v0
	v_mov_b32_e32 v83, v0
	v_mov_b32_e32 v84, v0
	v_mov_b32_e32 v85, v0
	v_mov_b32_e32 v86, v0
	v_mov_b32_e32 v87, v0
	v_mov_b32_e32 v88, v0
	v_mov_b32_e32 v89, v0
	v_mov_b32_e32 v90, v0
	v_mov_b32_e32 v91, v0
	v_mov_b32_e32 v92, v0
	v_mov_b32_e32 v93, v0
	v_mov_b32_e32 v94, v0
	v_mov_b32_e32 v95, v0
	v_mov_b32_e32 v112, v0
	v_mov_b32_e32 v113, v0
	v_mov_b32_e32 v114, v0
	v_mov_b32_e32 v115, v0
	v_mov_b32_e32 v116, v0
	v_mov_b32_e32 v117, v0
	v_mov_b32_e32 v118, v0
	v_mov_b32_e32 v119, v0
	v_mov_b32_e32 v120, v0
	v_mov_b32_e32 v121, v0
	v_mov_b32_e32 v122, v0
	v_mov_b32_e32 v123, v0
	v_mov_b32_e32 v124, v0
	v_mov_b32_e32 v125, v0
	v_mov_b32_e32 v126, v0
	v_mov_b32_e32 v127, v0

; #define SBAR() __builtin_amdgcn_sched_barrier(0)
; DEVI void phase_gemm_in(const Params& p, int l, char* lds) {
;     ...
;     for (int cg2 = 0; cg2 < 2; ++cg2) {
;       SBAR();
;       const int cb = n0 + wn * 128 + cg2 * 64;
;       int mode = 0;
;       if (cb < F_GK) mode = 1;
;       else if ((cb >= F_DQ && cb < F_DV) || cb == F_KR) mode = 2;
;       else if (cb >= F_GATE && cb < F_KR) mode = 3;
.LBB0_139:
	s_setprio 0
	s_waitcnt vmcnt(6)
	v_add_u32_e32 v138, s2, v194
	s_movk_i32 s2, 0x1ff
	v_cmp_lt_i32_e64 s[10:11], s2, v138
	s_mov_b64 s[2:3], 0
	s_mov_b64 s[8:9], 0
	s_and_saveexec_b64 s[6:7], s[10:11]
	s_cbranch_execz .LBB0_141
	v_add_u32_e32 v128, 0xfffff400, v138
	s_movk_i32 s2, 0x800
	v_cmp_gt_u32_e32 vcc, s2, v128
	s_movk_i32 s2, 0x2580
	v_cmp_eq_u32_e64 s[2:3], s2, v138
	s_or_b64 s[2:3], s[2:3], vcc
	v_add_u32_e32 v128, 0xffffe680, v138
	s_movk_i32 s8, 0xc00
	v_cmp_gt_u32_e32 vcc, s8, v128
	s_xor_b64 s[8:9], s[2:3], -1
	s_and_b64 s[12:13], s[8:9], vcc
	s_and_b64 s[8:9], s[2:3], exec
	s_and_b64 s[2:3], s[12:13], exec

; DEVI int otid() { int t = threadIdx.x; asm volatile("" : "+v"(t)); return t; }
; template <int MI, int NC>
; DEVI void gemm_kloop(f32x16 (&acc)[2 * NC][MI], const u16* __restrict__ A, long lda, const u16* __restrict__ Bt, long ldb, int K, char* lds) {
;   const int tid = otid(), wid = tid >> 6, lane = tid & 63, r32 = lane & 31, hi = lane >> 5;
;   const int wm = wid & 3, wn = wid >> 2;
;   constexpr int ABUF = 32768, BBUF = 16384 * NC;
;   char* As = lds; char* Bs = lds + 65536;
;   const int ch = tid & 7, rw = tid >> 3;
;   const int swz = ((ch ^ ((rw >> 1) & 7)) << 4);
;   u32x4 ra[2 * MI], rb[2 * NC];
;   const u16* Ap = A + (long)rw * lda + ch * 8;
;   const u16* Bp = Bt + (long)rw * ldb + ch * 8;
;     ...
; #pragma unroll
;   for (int i = 0; i < 2 * NC; ++i)
; #pragma unroll
;     for (int j = 0; j < MI; ++j)
; #pragma unroll
;       for (int r = 0; r < 16; ++r) acc[i][j][r] = 0.f;
;   const int KT = K >> 6;
;   const int grp = __builtin_amdgcn_readfirstlane(wid) >> 2;
;   const int rowa0 = wn * (64 * NC) + r32, rowb0 = wm * (32 * MI) + r32;
;   const int sa = (rowa0 >> 1) & 7, sb = (rowb0 >> 1) & 7;
.LBB0_599:
	s_and_b64 vcc, exec, s[12:13]
	s_cbranch_vccz .LBB0_603
	s_setprio 1
	s_lshl_b32 s9, s41, 2
	s_add_i32 s9, s29, s9
	s_sub_i32 s9, s9, s43
	s_sub_i32 s9, s9, s42
	s_lshl_b32 s10, s40, 2
	s_sub_i32 s9, s9, s10
	s_lshl_b32 s10, s9, 8
	s_ashr_i32 s11, s10, 31
	s_lshl_b64 s[10:11], s[10:11], 11
	s_nop 0
	v_lshl_add_u64 v[0:1], v[196:197], 0, s[10:11]
	v_lshl_add_u64 v[0:1], v[0:1], 0, v[192:193]
	v_lshl_add_u64 v[160:161], s[2:3], 0, v[0:1]
	v_lshl_add_u64 v[0:1], v[198:199], 0, v[192:193]
	v_lshl_add_u64 v[162:163], s[90:91], 0, v[0:1]
	v_mov_b32_e32 v0, 0
	s_mov_b64 s[10:11], 0
	s_mov_b32 s12, 0x8000
	v_mov_b32_e32 v1, v0
	v_mov_b32_e32 v2, v0
	v_mov_b32_e32 v3, v0
	v_mov_b32_e32 v4, v0
	v_mov_b32_e32 v5, v0
	v_mov_b32_e32 v6, v0
	v_mov_b32_e32 v7, v0
	v_mov_b32_e32 v8, v0
	v_mov_b32_e32 v9, v0
	v_mov_b32_e32 v10, v0
	v_mov_b32_e32 v11, v0
	v_mov_b32_e32 v12, v0
	v_mov_b32_e32 v13, v0
	v_mov_b32_e32 v14, v0
	v_mov_b32_e32 v15, v0
	v_mov_b32_e32 v32, v0
	v_mov_b32_e32 v33, v0
	v_mov_b32_e32 v34, v0
	v_mov_b32_e32 v35, v0
	v_mov_b32_e32 v36, v0
	v_mov_b32_e32 v37, v0
	v_mov_b32_e32 v38, v0
	v_mov_b32_e32 v39, v0
	v_mov_b32_e32 v40, v0
	v_mov_b32_e32 v41, v0
	v_mov_b32_e32 v42, v0
	v_mov_b32_e32 v43, v0
	v_mov_b32_e32 v44, v0
	v_mov_b32_e32 v45, v0
	v_mov_b32_e32 v46, v0
	v_mov_b32_e32 v47, v0
	v_mov_b32_e32 v16, v0
	v_mov_b32_e32 v17, v0
	v_mov_b32_e32 v18, v0
	v_mov_b32_e32 v19, v0
	v_mov_b32_e32 v20, v0
	v_mov_b32_e32 v21, v0
	v_mov_b32_e32 v22, v0
	v_mov_b32_e32 v23, v0
	v_mov_b32_e32 v24, v0
	v_mov_b32_e32 v25, v0
	v_mov_b32_e32 v26, v0
	v_mov_b32_e32 v27, v0
	v_mov_b32_e32 v28, v0
	v_mov_b32_e32 v29, v0
	v_mov_b32_e32 v30, v0
	v_mov_b32_e32 v31, v0
	v_mov_b32_e32 v48, v0
	v_mov_b32_e32 v49, v0
	v_mov_b32_e32 v50, v0
	v_mov_b32_e32 v51, v0
	v_mov_b32_e32 v52, v0
	v_mov_b32_e32 v53, v0
	v_mov_b32_e32 v54, v0
	v_mov_b32_e32 v55, v0
	v_mov_b32_e32 v56, v0
	v_mov_b32_e32 v57, v0
	v_mov_b32_e32 v58, v0
	v_mov_b32_e32 v59, v0
	v_mov_b32_e32 v60, v0
	v_mov_b32_e32 v61, v0
	v_mov_b32_e32 v62, v0
	v_mov_b32_e32 v63, v0
	v_mov_b32_e32 v64, v0
	v_mov_b32_e32 v65, v0
	v_mov_b32_e32 v66, v0
	v_mov_b32_e32 v67, v0
	v_mov_b32_e32 v68, v0
	v_mov_b32_e32 v69, v0
	v_mov_b32_e32 v70, v0
	v_mov_b32_e32 v71, v0
	v_mov_b32_e32 v72, v0
	v_mov_b32_e32 v73, v0
	v_mov_b32_e32 v74, v0
	v_mov_b32_e32 v75, v0
	v_mov_b32_e32 v76, v0
	v_mov_b32_e32 v77, v0
	v_mov_b32_e32 v78, v0
	v_mov_b32_e32 v79, v0
	v_mov_b32_e32 v96, v0
	v_mov_b32_e32 v97, v0
	v_mov_b32_e32 v98, v0
	v_mov_b32_e32 v99, v0
	v_mov_b32_e32 v100, v0
	v_mov_b32_e32 v101, v0
	v_mov_b32_e32 v102, v0
	v_mov_b32_e32 v103, v0
	v_mov_b32_e32 v104, v0
	v_mov_b32_e32 v105, v0
	v_mov_b32_e32 v106, v0
	v_mov_b32_e32 v107, v0
	v_mov_b32_e32 v108, v0
	v_mov_b32_e32 v109, v0
	v_mov_b32_e32 v110, v0
	v_mov_b32_e32 v111, v0
	v_mov_b32_e32 v80, v0
	v_mov_b32_e32 v81, v0
	v_mov_b32_e32 v82, v0
	v_mov_b32_e32 v83, v0
	v_mov_b32_e32 v84, v0
	v_mov_b32_e32 v85, v0
	v_mov_b32_e32 v86, v0
	v_mov_b32_e32 v87, v0
	v_mov_b32_e32 v88, v0
	v_mov_b32_e32 v89, v0
	v_mov_b32_e32 v90, v0
	v_mov_b32_e32 v91, v0
	v_mov_b32_e32 v92, v0
	v_mov_b32_e32 v93, v0
	v_mov_b32_e32 v94, v0
	v_mov_b32_e32 v95, v0
	v_mov_b32_e32 v112, v0
	v_mov_b32_e32 v113, v0
	v_mov_b32_e32 v114, v0
	v_mov_b32_e32 v115, v0
	v_mov_b32_e32 v116, v0
	v_mov_b32_e32 v117, v0
	v_mov_b32_e32 v118, v0
	v_mov_b32_e32 v119, v0
	v_mov_b32_e32 v120, v0
	v_mov_b32_e32 v121, v0
	v_mov_b32_e32 v122, v0
	v_mov_b32_e32 v123, v0
	v_mov_b32_e32 v124, v0
	v_mov_b32_e32 v125, v0
	v_mov_b32_e32 v126, v0
	v_mov_b32_e32 v127, v0

; DEVI void lds_put4(char* wl, int RS, int row, int col, float a, float b, float c, float d) { u32x2 w = {cvtpk(a, b), cvtpk(c, d)}; *(u32x2*)(wl + row * RS + col * 2) = w; }
; DEVI float siluf(float x) { return x / (1.f + expf(-x)); }
; DEVI void phase_gemm_f1(const Params& p, int l, char* lds) {
;     ...
;     char* wl = lds + wid * (64 * 144);
; #pragma unroll
;     for (int cg2 = 0; cg2 < 2; ++cg2) {
; #pragma unroll
;       for (int mi = 0; mi < 2; ++mi) {
; #pragma unroll
;         for (int q = 0; q < 4; ++q) {
;           float h[4];
; #pragma unroll
;           for (int j = 0; j < 4; ++j) h[j] = siluf(acc[2 * cg2][mi][q * 4 + j]) * acc[2 * cg2 + 1][mi][q * 4 + j];
;           lds_put4(wl, 144, mi * 32 + r32, cg2 * 32 + q * 8 + hi * 4, h[0], h[1], h[2], h[3]);
;         }
.LBB0_603:
	s_setprio 0
	s_waitcnt vmcnt(7)
	v_mul_f32_e32 v128, 0xbfb8aa3b, v112
	v_rndne_f32_e32 v129, v128
	v_sub_f32_e32 v130, v128, v129
	v_fma_f32 v128, v112, s54, -v128
	v_fmac_f32_e32 v128, 0xb2a5705f, v112
	v_add_f32_e32 v128, v130, v128
	v_exp_f32_e32 v128, v128
	v_cvt_i32_f32_e32 v129, v129
	v_cmp_nlt_f32_e32 vcc, s55, v112
	v_ldexp_f32 v128, v128, v129
	v_mul_f32_e32 v129, 0xbfb8aa3b, v113
	v_rndne_f32_e32 v130, v129
	v_sub_f32_e32 v131, v129, v130
	v_fma_f32 v129, v113, s54, -v129
	v_fmac_f32_e32 v129, 0xb2a5705f, v113
	v_add_f32_e32 v129, v131, v129
	v_exp_f32_e32 v129, v129
	v_cvt_i32_f32_e32 v130, v130
	v_cndmask_b32_e32 v128, 0, v128, vcc
	v_cmp_ngt_f32_e32 vcc, s56, v112
	v_ldexp_f32 v129, v129, v130
	s_nop 0
	v_cndmask_b32_e32 v128, v212, v128, vcc
	v_cmp_nlt_f32_e32 vcc, s55, v113
	s_nop 1
	v_cndmask_b32_e32 v129, 0, v129, vcc
	v_cmp_ngt_f32_e32 vcc, s56, v113
	s_nop 1
	v_cndmask_b32_e32 v129, v212, v129, vcc
	v_pk_add_f32 v[128:129], v[128:129], 1.0 op_sel_hi:[1,0]
	s_nop 0
	v_div_scale_f32 v130, s[10:11], v129, v129, v113
	v_rcp_f32_e32 v131, v130
	s_waitcnt vmcnt(5)
	v_fma_f32 v132, -v130, v131, 1.0
	v_fmac_f32_e32 v131, v132, v131
	v_div_scale_f32 v132, vcc, v113, v129, v113
	v_mul_f32_e32 v133, v132, v131
	v_fma_f32 v134, -v130, v133, v132
	v_fmac_f32_e32 v133, v134, v131
	v_fma_f32 v130, -v130, v133, v132
	v_div_fmas_f32 v130, v130, v131, v133
	v_div_fixup_f32 v113, v130, v129, v113
	v_div_scale_f32 v129, s[10:11], v128, v128, v112
	v_rcp_f32_e32 v130, v129
	s_nop 0
	v_fma_f32 v131, -v129, v130, 1.0
	v_fmac_f32_e32 v130, v131, v130
	v_div_scale_f32 v131, vcc, v112, v128, v112
	v_mul_f32_e32 v132, v131, v130
	v_fma_f32 v133, -v129, v132, v131
	v_fmac_f32_e32 v132, v133, v130
	v_fma_f32 v129, -v129, v132, v131
	v_div_fmas_f32 v129, v129, v130, v132
	v_div_fixup_f32 v112, v129, v128, v112
	v_pk_mul_f32 v[96:97], v[96:97], v[112:113]
	v_mul_f32_e32 v112, 0xbfb8aa3b, v114
	v_rndne_f32_e32 v113, v112
	v_sub_f32_e32 v128, v112, v113
	v_fma_f32 v112, v114, s54, -v112
	v_fmac_f32_e32 v112, 0xb2a5705f, v114
	v_add_f32_e32 v112, v128, v112
	v_exp_f32_e32 v112, v112
	v_cvt_i32_f32_e32 v113, v113
	v_cmp_nlt_f32_e32 vcc, s55, v114
	v_cvt_pk_bf16_f32 v96, v96, v97
	v_ldexp_f32 v112, v112, v113
	v_mul_f32_e32 v113, 0xbfb8aa3b, v115
	v_rndne_f32_e32 v128, v113
	v_sub_f32_e32 v129, v113, v128
	v_fma_f32 v113, v115, s54, -v113
	v_fmac_f32_e32 v113, 0xb2a5705f, v115
	v_add_f32_e32 v113, v129, v113
	v_exp_f32_e32 v113, v113
	v_cvt_i32_f32_e32 v128, v128
	v_cndmask_b32_e32 v112, 0, v112, vcc
	v_cmp_ngt_f32_e32 vcc, s56, v114
	v_ldexp_f32 v113, v113, v128
	s_nop 0
	v_cndmask_b32_e32 v112, v212, v112, vcc
	v_cmp_nlt_f32_e32 vcc, s55, v115
	s_nop 1
	v_cndmask_b32_e32 v113, 0, v113, vcc
	v_cmp_ngt_f32_e32 vcc, s56, v115
	s_nop 1
	v_cndmask_b32_e32 v113, v212, v113, vcc
	v_pk_add_f32 v[112:113], v[112:113], 1.0 op_sel_hi:[1,0]
	s_nop 0
	v_div_scale_f32 v128, s[10:11], v113, v113, v115
	v_rcp_f32_e32 v129, v128
	s_nop 0
	v_fma_f32 v130, -v128, v129, 1.0
	v_fmac_f32_e32 v129, v130, v129
	v_div_scale_f32 v130, vcc, v115, v113, v115
	v_mul_f32_e32 v131, v130, v129
	v_fma_f32 v132, -v128, v131, v130
	v_fmac_f32_e32 v131, v132, v129
	v_fma_f32 v128, -v128, v131, v130
	v_div_fmas_f32 v128, v128, v129, v131
	v_div_fixup_f32 v113, v128, v113, v115
	v_div_scale_f32 v115, s[10:11], v112, v112, v114
	v_rcp_f32_e32 v128, v115
	s_nop 0
	v_fma_f32 v129, -v115, v128, 1.0
	v_fmac_f32_e32 v128, v129, v128
	v_div_scale_f32 v129, vcc, v114, v112, v114
	v_mul_f32_e32 v130, v129, v128
	v_fma_f32 v131, -v115, v130, v129
	v_fmac_f32_e32 v130, v131, v128
	v_fma_f32 v115, -v115, v130, v129
	v_div_fmas_f32 v115, v115, v128, v130
	v_div_fixup_f32 v112, v115, v112, v114
	v_pk_mul_f32 v[98:99], v[98:99], v[112:113]
	v_cmp_nlt_f32_e32 vcc, s55, v116
	v_cvt_pk_bf16_f32 v97, v98, v99
	v_mul_f32_e32 v98, 0xbfb8aa3b, v116
	v_rndne_f32_e32 v99, v98
	v_sub_f32_e32 v112, v98, v99
	v_fma_f32 v98, v116, s54, -v98
	v_fmac_f32_e32 v98, 0xb2a5705f, v116
	v_add_f32_e32 v98, v112, v98
	v_exp_f32_e32 v98, v98
	v_cvt_i32_f32_e32 v99, v99
	v_ldexp_f32 v98, v98, v99
	v_mul_f32_e32 v99, 0xbfb8aa3b, v117
	v_rndne_f32_e32 v112, v99
	v_sub_f32_e32 v113, v99, v112
	v_fma_f32 v99, v117, s54, -v99
	v_fmac_f32_e32 v99, 0xb2a5705f, v117
	v_add_f32_e32 v99, v113, v99
	v_exp_f32_e32 v99, v99
	v_cvt_i32_f32_e32 v112, v112
	v_cndmask_b32_e32 v98, 0, v98, vcc
	v_cmp_ngt_f32_e32 vcc, s56, v116
	v_ldexp_f32 v99, v99, v112
	s_nop 0
	v_cndmask_b32_e32 v98, v212, v98, vcc
	v_cmp_nlt_f32_e32 vcc, s55, v117
	s_nop 1
	v_cndmask_b32_e32 v99, 0, v99, vcc
	v_cmp_ngt_f32_e32 vcc, s56, v117
	s_nop 1
	v_cndmask_b32_e32 v99, v212, v99, vcc
	v_pk_add_f32 v[98:99], v[98:99], 1.0 op_sel_hi:[1,0]
	s_nop 0
	v_div_scale_f32 v112, s[10:11], v99, v99, v117
	v_rcp_f32_e32 v113, v112
	s_nop 0
	v_fma_f32 v114, -v112, v113, 1.0
	v_fmac_f32_e32 v113, v114, v113
	v_div_scale_f32 v114, vcc, v117, v99, v117
	v_mul_f32_e32 v115, v114, v113
	v_fma_f32 v128, -v112, v115, v114
	v_fmac_f32_e32 v115, v128, v113
	v_fma_f32 v112, -v112, v115, v114
	v_div_fmas_f32 v112, v112, v113, v115
	v_div_fixup_f32 v99, v112, v99, v117
	v_div_scale_f32 v112, s[10:11], v98, v98, v116
	v_rcp_f32_e32 v113, v112
	s_nop 0
	v_fma_f32 v114, -v112, v113, 1.0
	v_fmac_f32_e32 v113, v114, v113
	v_div_scale_f32 v114, vcc, v116, v98, v116
	v_mul_f32_e32 v115, v114, v113
	v_fma_f32 v117, -v112, v115, v114
	v_fmac_f32_e32 v115, v117, v113
	v_fma_f32 v112, -v112, v115, v114
	v_div_fmas_f32 v112, v112, v113, v115
	v_div_fixup_f32 v98, v112, v98, v116
	v_pk_mul_f32 v[98:99], v[100:101], v[98:99]
	v_mul_f32_e32 v100, 0xbfb8aa3b, v118
	v_rndne_f32_e32 v101, v100
; DEVI void lds_put4(char* wl, int RS, int row, int col, float a, float b, float c, float d) { u32x2 w = {cvtpk(a, b), cvtpk(c, d)}; *(u32x2*)(wl + row * RS + col * 2) = w; }
; DEVI float siluf(float x) { return x / (1.f + expf(-x)); }
; DEVI void phase_gemm_f1(const Params& p, int l, char* lds) {
;     ...
;     char* wl = lds + wid * (64 * 144);
; #pragma unroll
;     for (int cg2 = 0; cg2 < 2; ++cg2) {
; #pragma unroll
;       for (int mi = 0; mi < 2; ++mi) {
; #pragma unroll
;         for (int q = 0; q < 4; ++q) {
;           float h[4];
; #pragma unroll
;           for (int j = 0; j < 4; ++j) h[j] = siluf(acc[2 * cg2][mi][q * 4 + j]) * acc[2 * cg2 + 1][mi][q * 4 + j];
;           lds_put4(wl, 144, mi * 32 + r32, cg2 * 32 + q * 8 + hi * 4, h[0], h[1], h[2], h[3]);
;         }
	v_sub_f32_e32 v112, v100, v101
	v_fma_f32 v100, v118, s54, -v100
	v_fmac_f32_e32 v100, 0xb2a5705f, v118
	v_add_f32_e32 v100, v112, v100
	v_exp_f32_e32 v100, v100
	v_cvt_i32_f32_e32 v101, v101
	v_cmp_nlt_f32_e32 vcc, s55, v118
	v_cvt_pk_bf16_f32 v98, v98, v99
	v_ldexp_f32 v100, v100, v101
	v_mul_f32_e32 v101, 0xbfb8aa3b, v119
	v_rndne_f32_e32 v112, v101
	v_sub_f32_e32 v113, v101, v112
	v_fma_f32 v101, v119, s54, -v101
	v_fmac_f32_e32 v101, 0xb2a5705f, v119
	v_add_f32_e32 v101, v113, v101
	v_exp_f32_e32 v101, v101
	v_cvt_i32_f32_e32 v112, v112
	v_cndmask_b32_e32 v100, 0, v100, vcc
	v_cmp_ngt_f32_e32 vcc, s56, v118
	v_ldexp_f32 v101, v101, v112
	s_nop 0
	v_cndmask_b32_e32 v100, v212, v100, vcc
	v_cmp_nlt_f32_e32 vcc, s55, v119
	s_nop 1
	v_cndmask_b32_e32 v101, 0, v101, vcc
	v_cmp_ngt_f32_e32 vcc, s56, v119
	s_nop 1
	v_cndmask_b32_e32 v101, v212, v101, vcc
	v_pk_add_f32 v[100:101], v[100:101], 1.0 op_sel_hi:[1,0]
	s_nop 0
	v_div_scale_f32 v112, s[10:11], v101, v101, v119
	v_rcp_f32_e32 v113, v112
	s_nop 0
	v_fma_f32 v114, -v112, v113, 1.0
	v_fmac_f32_e32 v113, v114, v113
	v_div_scale_f32 v114, vcc, v119, v101, v119
	v_mul_f32_e32 v115, v114, v113
	v_fma_f32 v116, -v112, v115, v114
	v_fmac_f32_e32 v115, v116, v113
	v_fma_f32 v112, -v112, v115, v114
	v_div_fmas_f32 v112, v112, v113, v115
	v_div_fixup_f32 v101, v112, v101, v119
	v_div_scale_f32 v112, s[10:11], v100, v100, v118
	v_rcp_f32_e32 v113, v112
	s_nop 0
	v_fma_f32 v114, -v112, v113, 1.0
	v_fmac_f32_e32 v113, v114, v113
	v_div_scale_f32 v114, vcc, v118, v100, v118
	v_mul_f32_e32 v115, v114, v113
	v_fma_f32 v116, -v112, v115, v114
	v_fmac_f32_e32 v115, v116, v113
	v_fma_f32 v112, -v112, v115, v114
	v_div_fmas_f32 v112, v112, v113, v115
	v_div_fixup_f32 v100, v112, v100, v118
	v_pk_mul_f32 v[100:101], v[102:103], v[100:101]
	v_cmp_nlt_f32_e32 vcc, s55, v120
	v_cvt_pk_bf16_f32 v99, v100, v101
	ds_write2_b64 v225, v[96:97], v[98:99] offset1:2
	v_mul_f32_e32 v96, 0xbfb8aa3b, v120
	v_rndne_f32_e32 v97, v96
	v_sub_f32_e32 v98, v96, v97
	v_fma_f32 v96, v120, s54, -v96
	v_fmac_f32_e32 v96, 0xb2a5705f, v120
	v_add_f32_e32 v96, v98, v96
	v_exp_f32_e32 v96, v96
	v_cvt_i32_f32_e32 v97, v97
	v_ldexp_f32 v96, v96, v97
	v_mul_f32_e32 v97, 0xbfb8aa3b, v121
	v_rndne_f32_e32 v98, v97
	v_sub_f32_e32 v99, v97, v98
	v_fma_f32 v97, v121, s54, -v97
	v_fmac_f32_e32 v97, 0xb2a5705f, v121
	v_add_f32_e32 v97, v99, v97
	v_exp_f32_e32 v97, v97
	v_cvt_i32_f32_e32 v98, v98
	v_cndmask_b32_e32 v96, 0, v96, vcc
	v_cmp_ngt_f32_e32 vcc, s56, v120
	v_ldexp_f32 v97, v97, v98
	s_nop 0
	v_cndmask_b32_e32 v96, v212, v96, vcc
	v_cmp_nlt_f32_e32 vcc, s55, v121
	s_nop 1
	v_cndmask_b32_e32 v97, 0, v97, vcc
	v_cmp_ngt_f32_e32 vcc, s56, v121
	s_nop 1
	v_cndmask_b32_e32 v97, v212, v97, vcc
	v_pk_add_f32 v[96:97], v[96:97], 1.0 op_sel_hi:[1,0]
	s_nop 0
	v_div_scale_f32 v98, s[10:11], v97, v97, v121
	v_rcp_f32_e32 v99, v98
	s_nop 0
	v_fma_f32 v100, -v98, v99, 1.0
	v_fmac_f32_e32 v99, v100, v99
	v_div_scale_f32 v100, vcc, v121, v97, v121
	v_mul_f32_e32 v101, v100, v99
	v_fma_f32 v102, -v98, v101, v100
	v_fmac_f32_e32 v101, v102, v99
	v_fma_f32 v98, -v98, v101, v100
	v_div_fmas_f32 v98, v98, v99, v101
	v_div_fixup_f32 v97, v98, v97, v121
	v_div_scale_f32 v98, s[10:11], v96, v96, v120
	v_rcp_f32_e32 v99, v98
	s_nop 0
	v_fma_f32 v100, -v98, v99, 1.0
	v_fmac_f32_e32 v99, v100, v99
	v_div_scale_f32 v100, vcc, v120, v96, v120
	v_mul_f32_e32 v101, v100, v99
	v_fma_f32 v102, -v98, v101, v100
	v_fmac_f32_e32 v101, v102, v99
	v_fma_f32 v98, -v98, v101, v100
	v_div_fmas_f32 v98, v98, v99, v101
	v_div_fixup_f32 v96, v98, v96, v120
	v_mul_f32_e32 v98, 0xbfb8aa3b, v122
	v_rndne_f32_e32 v99, v98
	v_sub_f32_e32 v100, v98, v99
	v_fma_f32 v98, v122, s54, -v98
	v_fmac_f32_e32 v98, 0xb2a5705f, v122
	v_add_f32_e32 v98, v100, v98
	v_exp_f32_e32 v98, v98
	v_cvt_i32_f32_e32 v99, v99
	v_cmp_nlt_f32_e32 vcc, s55, v122
	v_pk_mul_f32 v[96:97], v[104:105], v[96:97]
	v_ldexp_f32 v98, v98, v99
	v_mul_f32_e32 v99, 0xbfb8aa3b, v123
	v_rndne_f32_e32 v100, v99
	v_sub_f32_e32 v101, v99, v100
	v_fma_f32 v99, v123, s54, -v99
	v_fmac_f32_e32 v99, 0xb2a5705f, v123
	v_add_f32_e32 v99, v101, v99
	v_exp_f32_e32 v99, v99
	v_cvt_i32_f32_e32 v100, v100
	v_cndmask_b32_e32 v98, 0, v98, vcc
	v_cmp_ngt_f32_e32 vcc, s56, v122
	v_cvt_pk_bf16_f32 v96, v96, v97
	v_ldexp_f32 v99, v99, v100
	v_cndmask_b32_e32 v98, v212, v98, vcc
	v_cmp_nlt_f32_e32 vcc, s55, v123
	s_nop 1
	v_cndmask_b32_e32 v99, 0, v99, vcc
	v_cmp_ngt_f32_e32 vcc, s56, v123
	s_nop 1
	v_cndmask_b32_e32 v99, v212, v99, vcc
	v_pk_add_f32 v[98:99], v[98:99], 1.0 op_sel_hi:[1,0]
	s_nop 0
	v_div_scale_f32 v100, s[10:11], v99, v99, v123
	v_rcp_f32_e32 v101, v100
	s_nop 0
	v_fma_f32 v102, -v100, v101, 1.0
	v_fmac_f32_e32 v101, v102, v101
	v_div_scale_f32 v102, vcc, v123, v99, v123
	v_mul_f32_e32 v103, v102, v101
	v_fma_f32 v104, -v100, v103, v102
	v_fmac_f32_e32 v103, v104, v101
	v_fma_f32 v100, -v100, v103, v102
	v_div_fmas_f32 v100, v100, v101, v103
	v_div_fixup_f32 v99, v100, v99, v123
	v_div_scale_f32 v100, s[10:11], v98, v98, v122
	v_rcp_f32_e32 v101, v100
	s_nop 0
	v_fma_f32 v102, -v100, v101, 1.0
	v_fmac_f32_e32 v101, v102, v101
	v_div_scale_f32 v102, vcc, v122, v98, v122
	v_mul_f32_e32 v103, v102, v101
	v_fma_f32 v104, -v100, v103, v102
	v_fmac_f32_e32 v103, v104, v101
	v_fma_f32 v100, -v100, v103, v102
	v_div_fmas_f32 v100, v100, v101, v103
	v_div_fixup_f32 v98, v100, v98, v122
	v_pk_mul_f32 v[98:99], v[106:107], v[98:99]
	v_cmp_nlt_f32_e32 vcc, s55, v124
	v_cvt_pk_bf16_f32 v97, v98, v99
	v_mul_f32_e32 v98, 0xbfb8aa3b, v124
	v_rndne_f32_e32 v99, v98
	v_sub_f32_e32 v100, v98, v99
	v_fma_f32 v98, v124, s54, -v98
; DEVI void lds_put4(char* wl, int RS, int row, int col, float a, float b, float c, float d) { u32x2 w = {cvtpk(a, b), cvtpk(c, d)}; *(u32x2*)(wl + row * RS + col * 2) = w; }
; DEVI float siluf(float x) { return x / (1.f + expf(-x)); }
; DEVI void phase_gemm_f1(const Params& p, int l, char* lds) {
;     ...
;     char* wl = lds + wid * (64 * 144);
; #pragma unroll
;     for (int cg2 = 0; cg2 < 2; ++cg2) {
; #pragma unroll
;       for (int mi = 0; mi < 2; ++mi) {
; #pragma unroll
;         for (int q = 0; q < 4; ++q) {
;           float h[4];
; #pragma unroll
;           for (int j = 0; j < 4; ++j) h[j] = siluf(acc[2 * cg2][mi][q * 4 + j]) * acc[2 * cg2 + 1][mi][q * 4 + j];
;           lds_put4(wl, 144, mi * 32 + r32, cg2 * 32 + q * 8 + hi * 4, h[0], h[1], h[2], h[3]);
;         }
	v_fmac_f32_e32 v98, 0xb2a5705f, v124
	v_add_f32_e32 v98, v100, v98
	v_exp_f32_e32 v98, v98
	v_cvt_i32_f32_e32 v99, v99
	v_ldexp_f32 v98, v98, v99
	v_mul_f32_e32 v99, 0xbfb8aa3b, v125
	v_rndne_f32_e32 v100, v99
	v_sub_f32_e32 v101, v99, v100
	v_fma_f32 v99, v125, s54, -v99
	v_fmac_f32_e32 v99, 0xb2a5705f, v125
	v_add_f32_e32 v99, v101, v99
	v_exp_f32_e32 v99, v99
	v_cvt_i32_f32_e32 v100, v100
	v_cndmask_b32_e32 v98, 0, v98, vcc
	v_cmp_ngt_f32_e32 vcc, s56, v124
	v_ldexp_f32 v99, v99, v100
	s_nop 0
	v_cndmask_b32_e32 v98, v212, v98, vcc
	v_cmp_nlt_f32_e32 vcc, s55, v125
	s_nop 1
	v_cndmask_b32_e32 v99, 0, v99, vcc
	v_cmp_ngt_f32_e32 vcc, s56, v125
	s_nop 1
	v_cndmask_b32_e32 v99, v212, v99, vcc
	v_pk_add_f32 v[98:99], v[98:99], 1.0 op_sel_hi:[1,0]
	s_nop 0
	v_div_scale_f32 v100, s[10:11], v99, v99, v125
	v_rcp_f32_e32 v101, v100
	s_nop 0
	v_fma_f32 v102, -v100, v101, 1.0
	v_fmac_f32_e32 v101, v102, v101
	v_div_scale_f32 v102, vcc, v125, v99, v125
	v_mul_f32_e32 v103, v102, v101
	v_fma_f32 v104, -v100, v103, v102
	v_fmac_f32_e32 v103, v104, v101
	v_fma_f32 v100, -v100, v103, v102
	v_div_fmas_f32 v100, v100, v101, v103
	v_div_fixup_f32 v99, v100, v99, v125
	v_div_scale_f32 v100, s[10:11], v98, v98, v124
	v_rcp_f32_e32 v101, v100
	s_nop 0
	v_fma_f32 v102, -v100, v101, 1.0
	v_fmac_f32_e32 v101, v102, v101
	v_div_scale_f32 v102, vcc, v124, v98, v124
	v_mul_f32_e32 v103, v102, v101
	v_fma_f32 v104, -v100, v103, v102
	v_fmac_f32_e32 v103, v104, v101
	v_fma_f32 v100, -v100, v103, v102
	v_div_fmas_f32 v100, v100, v101, v103
	v_div_fixup_f32 v98, v100, v98, v124
	v_mul_f32_e32 v100, 0xbfb8aa3b, v126
	v_rndne_f32_e32 v101, v100
	v_sub_f32_e32 v102, v100, v101
	v_fma_f32 v100, v126, s54, -v100
	v_fmac_f32_e32 v100, 0xb2a5705f, v126
	v_add_f32_e32 v100, v102, v100
	v_exp_f32_e32 v100, v100
	v_cvt_i32_f32_e32 v101, v101
	v_cmp_nlt_f32_e32 vcc, s55, v126
	v_pk_mul_f32 v[98:99], v[108:109], v[98:99]
	v_ldexp_f32 v100, v100, v101
	v_mul_f32_e32 v101, 0xbfb8aa3b, v127
	v_rndne_f32_e32 v102, v101
	v_sub_f32_e32 v103, v101, v102
	v_fma_f32 v101, v127, s54, -v101
	v_fmac_f32_e32 v101, 0xb2a5705f, v127
	v_add_f32_e32 v101, v103, v101
	v_exp_f32_e32 v101, v101
	v_cvt_i32_f32_e32 v102, v102
	v_cndmask_b32_e32 v100, 0, v100, vcc
	v_cmp_ngt_f32_e32 vcc, s56, v126
	v_cvt_pk_bf16_f32 v98, v98, v99
	v_ldexp_f32 v101, v101, v102
	v_cndmask_b32_e32 v100, v212, v100, vcc
	v_cmp_nlt_f32_e32 vcc, s55, v127
	s_nop 1
	v_cndmask_b32_e32 v101, 0, v101, vcc
	v_cmp_ngt_f32_e32 vcc, s56, v127
	s_nop 1
	v_cndmask_b32_e32 v101, v212, v101, vcc
	v_pk_add_f32 v[100:101], v[100:101], 1.0 op_sel_hi:[1,0]
	s_nop 0
	v_div_scale_f32 v102, s[10:11], v101, v101, v127
	v_rcp_f32_e32 v103, v102
	s_nop 0
	v_fma_f32 v104, -v102, v103, 1.0
	v_fmac_f32_e32 v103, v104, v103
	v_div_scale_f32 v104, vcc, v127, v101, v127
	v_mul_f32_e32 v105, v104, v103
	v_fma_f32 v106, -v102, v105, v104
	v_fmac_f32_e32 v105, v106, v103
	v_fma_f32 v102, -v102, v105, v104
	v_div_fmas_f32 v102, v102, v103, v105
	v_div_fixup_f32 v101, v102, v101, v127
	v_div_scale_f32 v102, s[10:11], v100, v100, v126
	v_rcp_f32_e32 v103, v102
	s_nop 0
	v_fma_f32 v104, -v102, v103, 1.0
	v_fmac_f32_e32 v103, v104, v103
	v_div_scale_f32 v104, vcc, v126, v100, v126
	v_mul_f32_e32 v105, v104, v103
	v_fma_f32 v106, -v102, v105, v104
	v_fmac_f32_e32 v105, v106, v103
	v_fma_f32 v102, -v102, v105, v104
	v_div_fmas_f32 v102, v102, v103, v105
	v_div_fixup_f32 v100, v102, v100, v126
	v_pk_mul_f32 v[100:101], v[110:111], v[100:101]
	v_cmp_nlt_f32_e32 vcc, s55, v80
	v_cvt_pk_bf16_f32 v99, v100, v101
	ds_write2_b64 v225, v[96:97], v[98:99] offset0:4 offset1:6
	v_mul_f32_e32 v96, 0xbfb8aa3b, v80
	v_rndne_f32_e32 v97, v96
	v_sub_f32_e32 v98, v96, v97
	v_fma_f32 v96, v80, s54, -v96
	v_fmac_f32_e32 v96, 0xb2a5705f, v80
	v_add_f32_e32 v96, v98, v96
	v_exp_f32_e32 v96, v96
	v_cvt_i32_f32_e32 v97, v97
	v_ldexp_f32 v96, v96, v97
	v_mul_f32_e32 v97, 0xbfb8aa3b, v81
	v_rndne_f32_e32 v98, v97
	v_sub_f32_e32 v99, v97, v98
	v_fma_f32 v97, v81, s54, -v97
	v_fmac_f32_e32 v97, 0xb2a5705f, v81
	v_add_f32_e32 v97, v99, v97
	v_exp_f32_e32 v97, v97
	v_cvt_i32_f32_e32 v98, v98
	v_cndmask_b32_e32 v96, 0, v96, vcc
	v_cmp_ngt_f32_e32 vcc, s56, v80
	v_ldexp_f32 v97, v97, v98
	s_nop 0
	v_cndmask_b32_e32 v96, v212, v96, vcc
	v_cmp_nlt_f32_e32 vcc, s55, v81
	s_nop 1
	v_cndmask_b32_e32 v97, 0, v97, vcc
	v_cmp_ngt_f32_e32 vcc, s56, v81
	s_nop 1
	v_cndmask_b32_e32 v97, v212, v97, vcc
	v_pk_add_f32 v[96:97], v[96:97], 1.0 op_sel_hi:[1,0]
	s_nop 0
	v_div_scale_f32 v98, s[10:11], v97, v97, v81
	v_rcp_f32_e32 v99, v98
	s_nop 0
	v_fma_f32 v100, -v98, v99, 1.0
	v_fmac_f32_e32 v99, v100, v99
	v_div_scale_f32 v100, vcc, v81, v97, v81
	v_mul_f32_e32 v101, v100, v99
	v_fma_f32 v102, -v98, v101, v100
	v_fmac_f32_e32 v101, v102, v99
	v_fma_f32 v98, -v98, v101, v100
	v_div_fmas_f32 v98, v98, v99, v101
	v_div_fixup_f32 v81, v98, v97, v81
	v_div_scale_f32 v97, s[10:11], v96, v96, v80
	v_rcp_f32_e32 v98, v97
	s_nop 0
	v_fma_f32 v99, -v97, v98, 1.0
	v_fmac_f32_e32 v98, v99, v98
	v_div_scale_f32 v99, vcc, v80, v96, v80
	v_mul_f32_e32 v100, v99, v98
	v_fma_f32 v101, -v97, v100, v99
	v_fmac_f32_e32 v100, v101, v98
	v_fma_f32 v97, -v97, v100, v99
	v_div_fmas_f32 v97, v97, v98, v100
	v_div_fixup_f32 v80, v97, v96, v80
	v_pk_mul_f32 v[64:65], v[64:65], v[80:81]
	v_mul_f32_e32 v80, 0xbfb8aa3b, v82
	v_rndne_f32_e32 v81, v80
	v_sub_f32_e32 v96, v80, v81
	v_fma_f32 v80, v82, s54, -v80
	v_fmac_f32_e32 v80, 0xb2a5705f, v82
	v_add_f32_e32 v80, v96, v80
	v_exp_f32_e32 v80, v80
	v_cvt_i32_f32_e32 v81, v81
	v_cmp_nlt_f32_e32 vcc, s55, v82
	v_cvt_pk_bf16_f32 v64, v64, v65
	v_ldexp_f32 v80, v80, v81
; DEVI void lds_put4(char* wl, int RS, int row, int col, float a, float b, float c, float d) { u32x2 w = {cvtpk(a, b), cvtpk(c, d)}; *(u32x2*)(wl + row * RS + col * 2) = w; }
; DEVI float siluf(float x) { return x / (1.f + expf(-x)); }
; DEVI void phase_gemm_f1(const Params& p, int l, char* lds) {
;     ...
;     char* wl = lds + wid * (64 * 144);
; #pragma unroll
;     for (int cg2 = 0; cg2 < 2; ++cg2) {
; #pragma unroll
;       for (int mi = 0; mi < 2; ++mi) {
; #pragma unroll
;         for (int q = 0; q < 4; ++q) {
;           float h[4];
; #pragma unroll
;           for (int j = 0; j < 4; ++j) h[j] = siluf(acc[2 * cg2][mi][q * 4 + j]) * acc[2 * cg2 + 1][mi][q * 4 + j];
;           lds_put4(wl, 144, mi * 32 + r32, cg2 * 32 + q * 8 + hi * 4, h[0], h[1], h[2], h[3]);
;         }
	v_mul_f32_e32 v81, 0xbfb8aa3b, v83
	v_rndne_f32_e32 v96, v81
	v_sub_f32_e32 v97, v81, v96
	v_fma_f32 v81, v83, s54, -v81
	v_fmac_f32_e32 v81, 0xb2a5705f, v83
	v_add_f32_e32 v81, v97, v81
	v_exp_f32_e32 v81, v81
	v_cvt_i32_f32_e32 v96, v96
	v_cndmask_b32_e32 v80, 0, v80, vcc
	v_cmp_ngt_f32_e32 vcc, s56, v82
	v_ldexp_f32 v81, v81, v96
	s_nop 0
	v_cndmask_b32_e32 v80, v212, v80, vcc
	v_cmp_nlt_f32_e32 vcc, s55, v83
	s_nop 1
	v_cndmask_b32_e32 v81, 0, v81, vcc
	v_cmp_ngt_f32_e32 vcc, s56, v83
	s_nop 1
	v_cndmask_b32_e32 v81, v212, v81, vcc
	v_pk_add_f32 v[80:81], v[80:81], 1.0 op_sel_hi:[1,0]
	s_nop 0
	v_div_scale_f32 v96, s[10:11], v81, v81, v83
	v_rcp_f32_e32 v97, v96
	s_nop 0
	v_fma_f32 v98, -v96, v97, 1.0
	v_fmac_f32_e32 v97, v98, v97
	v_div_scale_f32 v98, vcc, v83, v81, v83
	v_mul_f32_e32 v99, v98, v97
	v_fma_f32 v100, -v96, v99, v98
	v_fmac_f32_e32 v99, v100, v97
	v_fma_f32 v96, -v96, v99, v98
	v_div_fmas_f32 v96, v96, v97, v99
	v_div_fixup_f32 v81, v96, v81, v83
	v_div_scale_f32 v83, s[10:11], v80, v80, v82
	v_rcp_f32_e32 v96, v83
	s_nop 0
	v_fma_f32 v97, -v83, v96, 1.0
	v_fmac_f32_e32 v96, v97, v96
	v_div_scale_f32 v97, vcc, v82, v80, v82
	v_mul_f32_e32 v98, v97, v96
	v_fma_f32 v99, -v83, v98, v97
	v_fmac_f32_e32 v98, v99, v96
	v_fma_f32 v83, -v83, v98, v97
	v_div_fmas_f32 v83, v83, v96, v98
	v_div_fixup_f32 v80, v83, v80, v82
	v_pk_mul_f32 v[66:67], v[66:67], v[80:81]
	v_cmp_nlt_f32_e32 vcc, s55, v84
	v_cvt_pk_bf16_f32 v65, v66, v67
	v_mul_f32_e32 v66, 0xbfb8aa3b, v84
	v_rndne_f32_e32 v67, v66
	v_sub_f32_e32 v80, v66, v67
	v_fma_f32 v66, v84, s54, -v66
	v_fmac_f32_e32 v66, 0xb2a5705f, v84
	v_add_f32_e32 v66, v80, v66
	v_exp_f32_e32 v66, v66
	v_cvt_i32_f32_e32 v67, v67
	v_ldexp_f32 v66, v66, v67
	v_mul_f32_e32 v67, 0xbfb8aa3b, v85
	v_rndne_f32_e32 v80, v67
	v_sub_f32_e32 v81, v67, v80
	v_fma_f32 v67, v85, s54, -v67
	v_fmac_f32_e32 v67, 0xb2a5705f, v85
	v_add_f32_e32 v67, v81, v67
	v_exp_f32_e32 v67, v67
	v_cvt_i32_f32_e32 v80, v80
	v_cndmask_b32_e32 v66, 0, v66, vcc
	v_cmp_ngt_f32_e32 vcc, s56, v84
	v_ldexp_f32 v67, v67, v80
	s_nop 0
	v_cndmask_b32_e32 v66, v212, v66, vcc
	v_cmp_nlt_f32_e32 vcc, s55, v85
	s_nop 1
	v_cndmask_b32_e32 v67, 0, v67, vcc
	v_cmp_ngt_f32_e32 vcc, s56, v85
	s_nop 1
	v_cndmask_b32_e32 v67, v212, v67, vcc
	v_pk_add_f32 v[66:67], v[66:67], 1.0 op_sel_hi:[1,0]
	s_nop 0
	v_div_scale_f32 v80, s[10:11], v67, v67, v85
	v_rcp_f32_e32 v81, v80
	s_nop 0
	v_fma_f32 v82, -v80, v81, 1.0
	v_fmac_f32_e32 v81, v82, v81
	v_div_scale_f32 v82, vcc, v85, v67, v85
	v_mul_f32_e32 v83, v82, v81
	v_fma_f32 v96, -v80, v83, v82
	v_fmac_f32_e32 v83, v96, v81
	v_fma_f32 v80, -v80, v83, v82
	v_div_fmas_f32 v80, v80, v81, v83
	v_div_fixup_f32 v67, v80, v67, v85
	v_div_scale_f32 v80, s[10:11], v66, v66, v84
	v_rcp_f32_e32 v81, v80
	s_nop 0
	v_fma_f32 v82, -v80, v81, 1.0
	v_fmac_f32_e32 v81, v82, v81
	v_div_scale_f32 v82, vcc, v84, v66, v84
	v_mul_f32_e32 v83, v82, v81
	v_fma_f32 v85, -v80, v83, v82
	v_fmac_f32_e32 v83, v85, v81
	v_fma_f32 v80, -v80, v83, v82
	v_div_fmas_f32 v80, v80, v81, v83
	v_div_fixup_f32 v66, v80, v66, v84
	v_pk_mul_f32 v[66:67], v[68:69], v[66:67]
	v_mul_f32_e32 v68, 0xbfb8aa3b, v86
	v_rndne_f32_e32 v69, v68
	v_sub_f32_e32 v80, v68, v69
	v_fma_f32 v68, v86, s54, -v68
	v_fmac_f32_e32 v68, 0xb2a5705f, v86
	v_add_f32_e32 v68, v80, v68
	v_exp_f32_e32 v68, v68
	v_cvt_i32_f32_e32 v69, v69
	v_cmp_nlt_f32_e32 vcc, s55, v86
	v_ldexp_f32 v68, v68, v69
	v_mul_f32_e32 v69, 0xbfb8aa3b, v87
	v_rndne_f32_e32 v80, v69
	v_sub_f32_e32 v81, v69, v80
	v_fma_f32 v69, v87, s54, -v69
	v_fmac_f32_e32 v69, 0xb2a5705f, v87
	v_add_f32_e32 v69, v81, v69
	v_exp_f32_e32 v69, v69
	v_cvt_i32_f32_e32 v80, v80
	v_cndmask_b32_e32 v68, 0, v68, vcc
	v_cmp_ngt_f32_e32 vcc, s56, v86
	v_ldexp_f32 v69, v69, v80
	s_nop 0
	v_cndmask_b32_e32 v68, v212, v68, vcc
	v_cmp_nlt_f32_e32 vcc, s55, v87
	s_nop 1
	v_cndmask_b32_e32 v69, 0, v69, vcc
	v_cmp_ngt_f32_e32 vcc, s56, v87
	s_nop 1
	v_cndmask_b32_e32 v69, v212, v69, vcc
	v_pk_add_f32 v[68:69], v[68:69], 1.0 op_sel_hi:[1,0]
	s_nop 0
	v_div_scale_f32 v80, s[10:11], v69, v69, v87
	v_rcp_f32_e32 v81, v80
	s_nop 0
	v_fma_f32 v82, -v80, v81, 1.0
	v_fmac_f32_e32 v81, v82, v81
	v_div_scale_f32 v82, vcc, v87, v69, v87
	v_mul_f32_e32 v83, v82, v81
	v_fma_f32 v84, -v80, v83, v82
	v_fmac_f32_e32 v83, v84, v81
	v_fma_f32 v80, -v80, v83, v82
	v_div_fmas_f32 v80, v80, v81, v83
	v_div_fixup_f32 v69, v80, v69, v87
	v_div_scale_f32 v80, s[10:11], v68, v68, v86
	v_rcp_f32_e32 v81, v80
	s_nop 0
	v_fma_f32 v82, -v80, v81, 1.0
	v_fmac_f32_e32 v81, v82, v81
	v_div_scale_f32 v82, vcc, v86, v68, v86
	v_mul_f32_e32 v83, v82, v81
	v_fma_f32 v84, -v80, v83, v82
	v_fmac_f32_e32 v83, v84, v81
	v_fma_f32 v80, -v80, v83, v82
	v_div_fmas_f32 v80, v80, v81, v83
	v_div_fixup_f32 v68, v80, v68, v86
	v_pk_mul_f32 v[68:69], v[70:71], v[68:69]
	v_cvt_pk_bf16_f32 v70, v66, v67
	v_cvt_pk_bf16_f32 v71, v68, v69
	v_add_u32_e32 v66, 0x1000, v225
	ds_write2_b64 v66, v[64:65], v[70:71] offset0:64 offset1:66
	v_mul_f32_e32 v64, 0xbfb8aa3b, v88
	v_rndne_f32_e32 v65, v64
	v_sub_f32_e32 v67, v64, v65
	v_fma_f32 v64, v88, s54, -v64
	v_fmac_f32_e32 v64, 0xb2a5705f, v88
	v_add_f32_e32 v64, v67, v64
	v_exp_f32_e32 v64, v64
	v_cvt_i32_f32_e32 v65, v65
	v_cmp_nlt_f32_e32 vcc, s55, v88
	v_ldexp_f32 v64, v64, v65
	v_mul_f32_e32 v65, 0xbfb8aa3b, v89
	v_rndne_f32_e32 v67, v65
	v_sub_f32_e32 v68, v65, v67
	v_fma_f32 v65, v89, s54, -v65
	v_fmac_f32_e32 v65, 0xb2a5705f, v89
	v_add_f32_e32 v65, v68, v65
	v_exp_f32_e32 v65, v65
	v_cvt_i32_f32_e32 v67, v67
	v_cndmask_b32_e32 v64, 0, v64, vcc
	v_cmp_ngt_f32_e32 vcc, s56, v88
	v_ldexp_f32 v65, v65, v67
	s_nop 0
; DEVI void lds_put4(char* wl, int RS, int row, int col, float a, float b, float c, float d) { u32x2 w = {cvtpk(a, b), cvtpk(c, d)}; *(u32x2*)(wl + row * RS + col * 2) = w; }
; DEVI float siluf(float x) { return x / (1.f + expf(-x)); }
; DEVI void phase_gemm_f1(const Params& p, int l, char* lds) {
;     ...
;     char* wl = lds + wid * (64 * 144);
; #pragma unroll
;     for (int cg2 = 0; cg2 < 2; ++cg2) {
; #pragma unroll
;       for (int mi = 0; mi < 2; ++mi) {
; #pragma unroll
;         for (int q = 0; q < 4; ++q) {
;           float h[4];
; #pragma unroll
;           for (int j = 0; j < 4; ++j) h[j] = siluf(acc[2 * cg2][mi][q * 4 + j]) * acc[2 * cg2 + 1][mi][q * 4 + j];
;           lds_put4(wl, 144, mi * 32 + r32, cg2 * 32 + q * 8 + hi * 4, h[0], h[1], h[2], h[3]);
;         }
	v_cndmask_b32_e32 v64, v212, v64, vcc
	v_cmp_nlt_f32_e32 vcc, s55, v89
	s_nop 1
	v_cndmask_b32_e32 v65, 0, v65, vcc
	v_cmp_ngt_f32_e32 vcc, s56, v89
	s_nop 1
	v_cndmask_b32_e32 v65, v212, v65, vcc
	v_pk_add_f32 v[64:65], v[64:65], 1.0 op_sel_hi:[1,0]
	s_nop 0
	v_div_scale_f32 v67, s[10:11], v65, v65, v89
	v_rcp_f32_e32 v68, v67
	s_nop 0
	v_fma_f32 v69, -v67, v68, 1.0
	v_fmac_f32_e32 v68, v69, v68
	v_div_scale_f32 v69, vcc, v89, v65, v89
	v_mul_f32_e32 v70, v69, v68
	v_fma_f32 v71, -v67, v70, v69
	v_fmac_f32_e32 v70, v71, v68
	v_fma_f32 v67, -v67, v70, v69
	v_div_fmas_f32 v67, v67, v68, v70
	v_div_fixup_f32 v65, v67, v65, v89
	v_div_scale_f32 v67, s[10:11], v64, v64, v88
	v_rcp_f32_e32 v68, v67
	s_nop 0
	v_fma_f32 v69, -v67, v68, 1.0
	v_fmac_f32_e32 v68, v69, v68
	v_div_scale_f32 v69, vcc, v88, v64, v88
	v_mul_f32_e32 v70, v69, v68
	v_fma_f32 v71, -v67, v70, v69
	v_fmac_f32_e32 v70, v71, v68
	v_fma_f32 v67, -v67, v70, v69
	v_div_fmas_f32 v67, v67, v68, v70
	v_div_fixup_f32 v64, v67, v64, v88
	v_mul_f32_e32 v67, 0xbfb8aa3b, v90
	v_rndne_f32_e32 v68, v67
	v_sub_f32_e32 v69, v67, v68
	v_fma_f32 v67, v90, s54, -v67
	v_fmac_f32_e32 v67, 0xb2a5705f, v90
	v_add_f32_e32 v67, v69, v67
	v_exp_f32_e32 v67, v67
	v_cvt_i32_f32_e32 v68, v68
	v_cmp_nlt_f32_e32 vcc, s55, v90
	v_pk_mul_f32 v[64:65], v[72:73], v[64:65]
	v_ldexp_f32 v67, v67, v68
	v_cndmask_b32_e32 v67, 0, v67, vcc
	v_cmp_ngt_f32_e32 vcc, s56, v90
	v_cvt_pk_bf16_f32 v64, v64, v65
	s_nop 0
	v_cndmask_b32_e32 v68, v212, v67, vcc
	v_mul_f32_e32 v67, 0xbfb8aa3b, v91
	v_rndne_f32_e32 v69, v67
	v_sub_f32_e32 v70, v67, v69
	v_fma_f32 v67, v91, s54, -v67
	v_fmac_f32_e32 v67, 0xb2a5705f, v91
	v_add_f32_e32 v67, v70, v67
	v_exp_f32_e32 v67, v67
	v_cvt_i32_f32_e32 v69, v69
	v_cmp_nlt_f32_e32 vcc, s55, v91
	v_ldexp_f32 v67, v67, v69
	s_nop 0
	v_cndmask_b32_e32 v67, 0, v67, vcc
	v_cmp_ngt_f32_e32 vcc, s56, v91
	s_nop 1
	v_cndmask_b32_e32 v69, v212, v67, vcc
	v_pk_add_f32 v[68:69], v[68:69], 1.0 op_sel_hi:[1,0]
	s_nop 0
	v_div_scale_f32 v67, s[10:11], v69, v69, v91
	v_rcp_f32_e32 v70, v67
	s_nop 0
	v_fma_f32 v71, -v67, v70, 1.0
	v_fmac_f32_e32 v70, v71, v70
	v_div_scale_f32 v71, vcc, v91, v69, v91
	v_mul_f32_e32 v72, v71, v70
	v_fma_f32 v73, -v67, v72, v71
	v_fmac_f32_e32 v72, v73, v70
	v_fma_f32 v67, -v67, v72, v71
	v_div_fmas_f32 v67, v67, v70, v72
	v_div_fixup_f32 v69, v67, v69, v91
	v_div_scale_f32 v67, s[10:11], v68, v68, v90
	v_rcp_f32_e32 v70, v67
	s_nop 0
	v_fma_f32 v71, -v67, v70, 1.0
	v_fmac_f32_e32 v70, v71, v70
	v_div_scale_f32 v71, vcc, v90, v68, v90
	v_mul_f32_e32 v72, v71, v70
	v_fma_f32 v73, -v67, v72, v71
	v_fmac_f32_e32 v72, v73, v70
	v_fma_f32 v67, -v67, v72, v71
	v_div_fmas_f32 v67, v67, v70, v72
	v_div_fixup_f32 v68, v67, v68, v90
	v_pk_mul_f32 v[68:69], v[74:75], v[68:69]
	v_mul_f32_e32 v67, 0xbfb8aa3b, v92
	v_cvt_pk_bf16_f32 v65, v68, v69
	v_rndne_f32_e32 v68, v67
	v_sub_f32_e32 v69, v67, v68
	v_fma_f32 v67, v92, s54, -v67
	v_fmac_f32_e32 v67, 0xb2a5705f, v92
	v_add_f32_e32 v67, v69, v67
	v_exp_f32_e32 v67, v67
	v_cvt_i32_f32_e32 v68, v68
	v_cmp_nlt_f32_e32 vcc, s55, v92
	v_ldexp_f32 v67, v67, v68
	s_nop 0
	v_cndmask_b32_e32 v67, 0, v67, vcc
	v_cmp_ngt_f32_e32 vcc, s56, v92
	s_nop 1
	v_cndmask_b32_e32 v68, v212, v67, vcc
	v_mul_f32_e32 v67, 0xbfb8aa3b, v93
	v_rndne_f32_e32 v69, v67
	v_sub_f32_e32 v70, v67, v69
	v_fma_f32 v67, v93, s54, -v67
	v_fmac_f32_e32 v67, 0xb2a5705f, v93
	v_add_f32_e32 v67, v70, v67
	v_exp_f32_e32 v67, v67
	v_cvt_i32_f32_e32 v69, v69
	v_cmp_nlt_f32_e32 vcc, s55, v93
	v_ldexp_f32 v67, v67, v69
	s_nop 0
	v_cndmask_b32_e32 v67, 0, v67, vcc
	v_cmp_ngt_f32_e32 vcc, s56, v93
	s_nop 1
	v_cndmask_b32_e32 v69, v212, v67, vcc
	v_pk_add_f32 v[68:69], v[68:69], 1.0 op_sel_hi:[1,0]
	s_nop 0
	v_div_scale_f32 v67, s[10:11], v69, v69, v93
	v_rcp_f32_e32 v70, v67
	s_nop 0
	v_fma_f32 v71, -v67, v70, 1.0
	v_fmac_f32_e32 v70, v71, v70
	v_div_scale_f32 v71, vcc, v93, v69, v93
	v_mul_f32_e32 v72, v71, v70
	v_fma_f32 v73, -v67, v72, v71
	v_fmac_f32_e32 v72, v73, v70
	v_fma_f32 v67, -v67, v72, v71
	v_div_fmas_f32 v67, v67, v70, v72
	v_div_fixup_f32 v69, v67, v69, v93
	v_div_scale_f32 v67, s[10:11], v68, v68, v92
	v_rcp_f32_e32 v70, v67
	s_nop 0
	v_fma_f32 v71, -v67, v70, 1.0
	v_fmac_f32_e32 v70, v71, v70
	v_div_scale_f32 v71, vcc, v92, v68, v92
	v_mul_f32_e32 v72, v71, v70
	v_fma_f32 v73, -v67, v72, v71
	v_fmac_f32_e32 v72, v73, v70
	v_fma_f32 v67, -v67, v72, v71
	v_div_fmas_f32 v67, v67, v70, v72
	v_div_fixup_f32 v68, v67, v68, v92
	v_mul_f32_e32 v67, 0xbfb8aa3b, v94
	v_rndne_f32_e32 v70, v67
	v_sub_f32_e32 v71, v67, v70
	v_fma_f32 v67, v94, s54, -v67
	v_fmac_f32_e32 v67, 0xb2a5705f, v94
	v_add_f32_e32 v67, v71, v67
	v_exp_f32_e32 v67, v67
	v_cvt_i32_f32_e32 v70, v70
	v_cmp_nlt_f32_e32 vcc, s55, v94
	v_pk_mul_f32 v[68:69], v[76:77], v[68:69]
	v_ldexp_f32 v67, v67, v70
	v_cndmask_b32_e32 v67, 0, v67, vcc
	v_cmp_ngt_f32_e32 vcc, s56, v94
	v_cvt_pk_bf16_f32 v68, v68, v69
	s_nop 0
	v_cndmask_b32_e32 v70, v212, v67, vcc
	v_mul_f32_e32 v67, 0xbfb8aa3b, v95
	v_rndne_f32_e32 v71, v67
	v_sub_f32_e32 v72, v67, v71
	v_fma_f32 v67, v95, s54, -v67
	v_fmac_f32_e32 v67, 0xb2a5705f, v95
	v_add_f32_e32 v67, v72, v67
	v_exp_f32_e32 v67, v67
	v_cvt_i32_f32_e32 v71, v71
	v_cmp_nlt_f32_e32 vcc, s55, v95
	v_ldexp_f32 v67, v67, v71
	s_nop 0
	v_cndmask_b32_e32 v67, 0, v67, vcc
	v_cmp_ngt_f32_e32 vcc, s56, v95
	s_nop 1
	v_cndmask_b32_e32 v71, v212, v67, vcc
	v_pk_add_f32 v[70:71], v[70:71], 1.0 op_sel_hi:[1,0]
	s_nop 0
	v_div_scale_f32 v67, s[10:11], v71, v71, v95
	v_rcp_f32_e32 v72, v67
	s_nop 0
	v_fma_f32 v73, -v67, v72, 1.0
	v_fmac_f32_e32 v72, v73, v72
	v_div_scale_f32 v73, vcc, v95, v71, v95
; DEVI void lds_put4(char* wl, int RS, int row, int col, float a, float b, float c, float d) { u32x2 w = {cvtpk(a, b), cvtpk(c, d)}; *(u32x2*)(wl + row * RS + col * 2) = w; }
; DEVI float siluf(float x) { return x / (1.f + expf(-x)); }
; DEVI void phase_gemm_f1(const Params& p, int l, char* lds) {
;     ...
;     char* wl = lds + wid * (64 * 144);
; #pragma unroll
;     for (int cg2 = 0; cg2 < 2; ++cg2) {
; #pragma unroll
;       for (int mi = 0; mi < 2; ++mi) {
; #pragma unroll
;         for (int q = 0; q < 4; ++q) {
;           float h[4];
; #pragma unroll
;           for (int j = 0; j < 4; ++j) h[j] = siluf(acc[2 * cg2][mi][q * 4 + j]) * acc[2 * cg2 + 1][mi][q * 4 + j];
;           lds_put4(wl, 144, mi * 32 + r32, cg2 * 32 + q * 8 + hi * 4, h[0], h[1], h[2], h[3]);
;         }
	v_mul_f32_e32 v74, v73, v72
	v_fma_f32 v75, -v67, v74, v73
	v_fmac_f32_e32 v74, v75, v72
	v_fma_f32 v67, -v67, v74, v73
	v_div_fmas_f32 v67, v67, v72, v74
	v_div_fixup_f32 v71, v67, v71, v95
	v_div_scale_f32 v67, s[10:11], v70, v70, v94
	v_rcp_f32_e32 v72, v67
	s_nop 0
	v_fma_f32 v73, -v67, v72, 1.0
	v_fmac_f32_e32 v72, v73, v72
	v_div_scale_f32 v73, vcc, v94, v70, v94
	v_mul_f32_e32 v74, v73, v72
	v_fma_f32 v75, -v67, v74, v73
	v_fmac_f32_e32 v74, v75, v72
	v_fma_f32 v67, -v67, v74, v73
	v_div_fmas_f32 v67, v67, v72, v74
	v_div_fixup_f32 v70, v67, v70, v94
	v_pk_mul_f32 v[70:71], v[78:79], v[70:71]
	v_cmp_nlt_f32_e32 vcc, s55, v48
	v_cvt_pk_bf16_f32 v69, v70, v71
	ds_write2_b64 v66, v[64:65], v[68:69] offset0:68 offset1:70
	v_mul_f32_e32 v64, 0xbfb8aa3b, v48
	v_rndne_f32_e32 v65, v64
	v_sub_f32_e32 v67, v64, v65
	v_fma_f32 v64, v48, s54, -v64
	v_fmac_f32_e32 v64, 0xb2a5705f, v48
	v_add_f32_e32 v64, v67, v64
	v_exp_f32_e32 v64, v64
	v_cvt_i32_f32_e32 v65, v65
	v_ldexp_f32 v64, v64, v65
	v_mul_f32_e32 v65, 0xbfb8aa3b, v49
	v_rndne_f32_e32 v67, v65
	v_sub_f32_e32 v68, v65, v67
	v_fma_f32 v65, v49, s54, -v65
	v_fmac_f32_e32 v65, 0xb2a5705f, v49
	v_add_f32_e32 v65, v68, v65
	v_exp_f32_e32 v65, v65
	v_cvt_i32_f32_e32 v67, v67
	v_cndmask_b32_e32 v64, 0, v64, vcc
	v_cmp_ngt_f32_e32 vcc, s56, v48
	v_ldexp_f32 v65, v65, v67
	s_nop 0
	v_cndmask_b32_e32 v64, v212, v64, vcc
	v_cmp_nlt_f32_e32 vcc, s55, v49
	s_nop 1
	v_cndmask_b32_e32 v65, 0, v65, vcc
	v_cmp_ngt_f32_e32 vcc, s56, v49
	s_nop 1
	v_cndmask_b32_e32 v65, v212, v65, vcc
	v_pk_add_f32 v[64:65], v[64:65], 1.0 op_sel_hi:[1,0]
	s_nop 0
	v_div_scale_f32 v67, s[10:11], v65, v65, v49
	v_rcp_f32_e32 v68, v67
	s_nop 0
	v_fma_f32 v69, -v67, v68, 1.0
	v_fmac_f32_e32 v68, v69, v68
	v_div_scale_f32 v69, vcc, v49, v65, v49
	v_mul_f32_e32 v70, v69, v68
	v_fma_f32 v71, -v67, v70, v69
	v_fmac_f32_e32 v70, v71, v68
	v_fma_f32 v67, -v67, v70, v69
	v_div_fmas_f32 v67, v67, v68, v70
	v_div_fixup_f32 v49, v67, v65, v49
	v_div_scale_f32 v65, s[10:11], v64, v64, v48
	v_rcp_f32_e32 v67, v65
	s_nop 0
	v_fma_f32 v68, -v65, v67, 1.0
	v_fmac_f32_e32 v67, v68, v67
	v_div_scale_f32 v68, vcc, v48, v64, v48
	v_mul_f32_e32 v69, v68, v67
	v_fma_f32 v70, -v65, v69, v68
	v_fmac_f32_e32 v69, v70, v67
	v_fma_f32 v65, -v65, v69, v68
	v_div_fmas_f32 v65, v65, v67, v69
	v_div_fixup_f32 v48, v65, v64, v48
	v_pk_mul_f32 v[32:33], v[32:33], v[48:49]
	v_mul_f32_e32 v48, 0xbfb8aa3b, v50
	v_rndne_f32_e32 v49, v48
	v_sub_f32_e32 v64, v48, v49
	v_fma_f32 v48, v50, s54, -v48
	v_fmac_f32_e32 v48, 0xb2a5705f, v50
	v_add_f32_e32 v48, v64, v48
	v_exp_f32_e32 v48, v48
	v_cvt_i32_f32_e32 v49, v49
	v_cmp_nlt_f32_e32 vcc, s55, v50
	v_cvt_pk_bf16_f32 v32, v32, v33
	v_ldexp_f32 v48, v48, v49
	v_mul_f32_e32 v49, 0xbfb8aa3b, v51
	v_rndne_f32_e32 v64, v49
	v_sub_f32_e32 v65, v49, v64
	v_fma_f32 v49, v51, s54, -v49
	v_fmac_f32_e32 v49, 0xb2a5705f, v51
	v_add_f32_e32 v49, v65, v49
	v_exp_f32_e32 v49, v49
	v_cvt_i32_f32_e32 v64, v64
	v_cndmask_b32_e32 v48, 0, v48, vcc
	v_cmp_ngt_f32_e32 vcc, s56, v50
	v_ldexp_f32 v49, v49, v64
	s_nop 0
	v_cndmask_b32_e32 v48, v212, v48, vcc
	v_cmp_nlt_f32_e32 vcc, s55, v51
	s_nop 1
	v_cndmask_b32_e32 v49, 0, v49, vcc
	v_cmp_ngt_f32_e32 vcc, s56, v51
	s_nop 1
	v_cndmask_b32_e32 v49, v212, v49, vcc
	v_pk_add_f32 v[48:49], v[48:49], 1.0 op_sel_hi:[1,0]
	s_nop 0
	v_div_scale_f32 v64, s[10:11], v49, v49, v51
	v_rcp_f32_e32 v65, v64
	s_nop 0
	v_fma_f32 v67, -v64, v65, 1.0
	v_fmac_f32_e32 v65, v67, v65
	v_div_scale_f32 v67, vcc, v51, v49, v51
	v_mul_f32_e32 v68, v67, v65
	v_fma_f32 v69, -v64, v68, v67
	v_fmac_f32_e32 v68, v69, v65
	v_fma_f32 v64, -v64, v68, v67
	v_div_fmas_f32 v64, v64, v65, v68
	v_div_fixup_f32 v49, v64, v49, v51
	v_div_scale_f32 v51, s[10:11], v48, v48, v50
	v_rcp_f32_e32 v64, v51
	s_nop 0
	v_fma_f32 v65, -v51, v64, 1.0
	v_fmac_f32_e32 v64, v65, v64
	v_div_scale_f32 v65, vcc, v50, v48, v50
	v_mul_f32_e32 v67, v65, v64
	v_fma_f32 v68, -v51, v67, v65
	v_fmac_f32_e32 v67, v68, v64
	v_fma_f32 v51, -v51, v67, v65
	v_div_fmas_f32 v51, v51, v64, v67
	v_div_fixup_f32 v48, v51, v48, v50
	v_pk_mul_f32 v[34:35], v[34:35], v[48:49]
	v_cmp_nlt_f32_e32 vcc, s55, v52
	v_cvt_pk_bf16_f32 v33, v34, v35
	v_mul_f32_e32 v34, 0xbfb8aa3b, v52
	v_rndne_f32_e32 v35, v34
	v_sub_f32_e32 v48, v34, v35
	v_fma_f32 v34, v52, s54, -v34
	v_fmac_f32_e32 v34, 0xb2a5705f, v52
	v_add_f32_e32 v34, v48, v34
	v_exp_f32_e32 v34, v34
	v_cvt_i32_f32_e32 v35, v35
	v_ldexp_f32 v34, v34, v35
	v_mul_f32_e32 v35, 0xbfb8aa3b, v53
	v_rndne_f32_e32 v48, v35
	v_sub_f32_e32 v49, v35, v48
	v_fma_f32 v35, v53, s54, -v35
	v_fmac_f32_e32 v35, 0xb2a5705f, v53
	v_add_f32_e32 v35, v49, v35
	v_exp_f32_e32 v35, v35
	v_cvt_i32_f32_e32 v48, v48
	v_cndmask_b32_e32 v34, 0, v34, vcc
	v_cmp_ngt_f32_e32 vcc, s56, v52
	v_ldexp_f32 v35, v35, v48
	s_nop 0
	v_cndmask_b32_e32 v34, v212, v34, vcc
	v_cmp_nlt_f32_e32 vcc, s55, v53
	s_nop 1
	v_cndmask_b32_e32 v35, 0, v35, vcc
	v_cmp_ngt_f32_e32 vcc, s56, v53
	s_nop 1
	v_cndmask_b32_e32 v35, v212, v35, vcc
	v_pk_add_f32 v[34:35], v[34:35], 1.0 op_sel_hi:[1,0]
	s_nop 0
	v_div_scale_f32 v48, s[10:11], v35, v35, v53
	v_rcp_f32_e32 v49, v48
	s_nop 0
	v_fma_f32 v50, -v48, v49, 1.0
	v_fmac_f32_e32 v49, v50, v49
	v_div_scale_f32 v50, vcc, v53, v35, v53
	v_mul_f32_e32 v51, v50, v49
	v_fma_f32 v64, -v48, v51, v50
	v_fmac_f32_e32 v51, v64, v49
	v_fma_f32 v48, -v48, v51, v50
	v_div_fmas_f32 v48, v48, v49, v51
	v_div_fixup_f32 v35, v48, v35, v53
	v_div_scale_f32 v48, s[10:11], v34, v34, v52
	v_rcp_f32_e32 v49, v48
	s_nop 0
	v_fma_f32 v50, -v48, v49, 1.0
	v_fmac_f32_e32 v49, v50, v49
	v_div_scale_f32 v50, vcc, v52, v34, v52
	v_mul_f32_e32 v51, v50, v49
; DEVI void lds_put4(char* wl, int RS, int row, int col, float a, float b, float c, float d) { u32x2 w = {cvtpk(a, b), cvtpk(c, d)}; *(u32x2*)(wl + row * RS + col * 2) = w; }
; DEVI float siluf(float x) { return x / (1.f + expf(-x)); }
; DEVI void phase_gemm_f1(const Params& p, int l, char* lds) {
;     ...
;     char* wl = lds + wid * (64 * 144);
; #pragma unroll
;     for (int cg2 = 0; cg2 < 2; ++cg2) {
; #pragma unroll
;       for (int mi = 0; mi < 2; ++mi) {
; #pragma unroll
;         for (int q = 0; q < 4; ++q) {
;           float h[4];
; #pragma unroll
;           for (int j = 0; j < 4; ++j) h[j] = siluf(acc[2 * cg2][mi][q * 4 + j]) * acc[2 * cg2 + 1][mi][q * 4 + j];
;           lds_put4(wl, 144, mi * 32 + r32, cg2 * 32 + q * 8 + hi * 4, h[0], h[1], h[2], h[3]);
;         }
	v_fma_f32 v53, -v48, v51, v50
	v_fmac_f32_e32 v51, v53, v49
	v_fma_f32 v48, -v48, v51, v50
	v_div_fmas_f32 v48, v48, v49, v51
	v_div_fixup_f32 v34, v48, v34, v52
	v_pk_mul_f32 v[34:35], v[36:37], v[34:35]
	v_mul_f32_e32 v36, 0xbfb8aa3b, v54
	v_rndne_f32_e32 v37, v36
	v_sub_f32_e32 v48, v36, v37
	v_fma_f32 v36, v54, s54, -v36
	v_fmac_f32_e32 v36, 0xb2a5705f, v54
	v_add_f32_e32 v36, v48, v36
	v_exp_f32_e32 v36, v36
	v_cvt_i32_f32_e32 v37, v37
	v_cmp_nlt_f32_e32 vcc, s55, v54
	v_cvt_pk_bf16_f32 v34, v34, v35
	v_ldexp_f32 v36, v36, v37
	v_mul_f32_e32 v37, 0xbfb8aa3b, v55
	v_rndne_f32_e32 v48, v37
	v_sub_f32_e32 v49, v37, v48
	v_fma_f32 v37, v55, s54, -v37
	v_fmac_f32_e32 v37, 0xb2a5705f, v55
	v_add_f32_e32 v37, v49, v37
	v_exp_f32_e32 v37, v37
	v_cvt_i32_f32_e32 v48, v48
	v_cndmask_b32_e32 v36, 0, v36, vcc
	v_cmp_ngt_f32_e32 vcc, s56, v54
	v_ldexp_f32 v37, v37, v48
	s_nop 0
	v_cndmask_b32_e32 v36, v212, v36, vcc
	v_cmp_nlt_f32_e32 vcc, s55, v55
	s_nop 1
	v_cndmask_b32_e32 v37, 0, v37, vcc
	v_cmp_ngt_f32_e32 vcc, s56, v55
	s_nop 1
	v_cndmask_b32_e32 v37, v212, v37, vcc
	v_pk_add_f32 v[36:37], v[36:37], 1.0 op_sel_hi:[1,0]
	s_nop 0
	v_div_scale_f32 v48, s[10:11], v37, v37, v55
	v_rcp_f32_e32 v49, v48
	s_nop 0
	v_fma_f32 v50, -v48, v49, 1.0
	v_fmac_f32_e32 v49, v50, v49
	v_div_scale_f32 v50, vcc, v55, v37, v55
	v_mul_f32_e32 v51, v50, v49
	v_fma_f32 v52, -v48, v51, v50
	v_fmac_f32_e32 v51, v52, v49
	v_fma_f32 v48, -v48, v51, v50
	v_div_fmas_f32 v48, v48, v49, v51
	v_div_fixup_f32 v37, v48, v37, v55
	v_div_scale_f32 v48, s[10:11], v36, v36, v54
	v_rcp_f32_e32 v49, v48
	s_nop 0
	v_fma_f32 v50, -v48, v49, 1.0
	v_fmac_f32_e32 v49, v50, v49
	v_div_scale_f32 v50, vcc, v54, v36, v54
	v_mul_f32_e32 v51, v50, v49
	v_fma_f32 v52, -v48, v51, v50
	v_fmac_f32_e32 v51, v52, v49
	v_fma_f32 v48, -v48, v51, v50
	v_div_fmas_f32 v48, v48, v49, v51
	v_div_fixup_f32 v36, v48, v36, v54
	v_pk_mul_f32 v[36:37], v[38:39], v[36:37]
	v_cmp_nlt_f32_e32 vcc, s55, v56
	v_cvt_pk_bf16_f32 v35, v36, v37
	ds_write2_b64 v225, v[32:33], v[34:35] offset0:8 offset1:10
	v_mul_f32_e32 v32, 0xbfb8aa3b, v56
	v_rndne_f32_e32 v33, v32
	v_sub_f32_e32 v34, v32, v33
	v_fma_f32 v32, v56, s54, -v32
	v_fmac_f32_e32 v32, 0xb2a5705f, v56
	v_add_f32_e32 v32, v34, v32
	v_exp_f32_e32 v32, v32
	v_cvt_i32_f32_e32 v33, v33
	v_ldexp_f32 v32, v32, v33
	v_mul_f32_e32 v33, 0xbfb8aa3b, v57
	v_rndne_f32_e32 v34, v33
	v_sub_f32_e32 v35, v33, v34
	v_fma_f32 v33, v57, s54, -v33
	v_fmac_f32_e32 v33, 0xb2a5705f, v57
	v_add_f32_e32 v33, v35, v33
	v_exp_f32_e32 v33, v33
	v_cvt_i32_f32_e32 v34, v34
	v_cndmask_b32_e32 v32, 0, v32, vcc
	v_cmp_ngt_f32_e32 vcc, s56, v56
	v_ldexp_f32 v33, v33, v34
	s_nop 0
	v_cndmask_b32_e32 v32, v212, v32, vcc
	v_cmp_nlt_f32_e32 vcc, s55, v57
	s_nop 1
	v_cndmask_b32_e32 v33, 0, v33, vcc
	v_cmp_ngt_f32_e32 vcc, s56, v57
	s_nop 1
	v_cndmask_b32_e32 v33, v212, v33, vcc
	v_pk_add_f32 v[32:33], v[32:33], 1.0 op_sel_hi:[1,0]
	s_nop 0
	v_div_scale_f32 v34, s[10:11], v33, v33, v57
	v_rcp_f32_e32 v35, v34
	s_nop 0
	v_fma_f32 v36, -v34, v35, 1.0
	v_fmac_f32_e32 v35, v36, v35
	v_div_scale_f32 v36, vcc, v57, v33, v57
	v_mul_f32_e32 v37, v36, v35
	v_fma_f32 v38, -v34, v37, v36
	v_fmac_f32_e32 v37, v38, v35
	v_fma_f32 v34, -v34, v37, v36
	v_div_fmas_f32 v34, v34, v35, v37
	v_div_fixup_f32 v33, v34, v33, v57
	v_div_scale_f32 v34, s[10:11], v32, v32, v56
	v_rcp_f32_e32 v35, v34
	s_nop 0
	v_fma_f32 v36, -v34, v35, 1.0
	v_fmac_f32_e32 v35, v36, v35
	v_div_scale_f32 v36, vcc, v56, v32, v56
	v_mul_f32_e32 v37, v36, v35
	v_fma_f32 v38, -v34, v37, v36
	v_fmac_f32_e32 v37, v38, v35
	v_fma_f32 v34, -v34, v37, v36
	v_div_fmas_f32 v34, v34, v35, v37
	v_div_fixup_f32 v32, v34, v32, v56
	v_mul_f32_e32 v34, 0xbfb8aa3b, v58
	v_rndne_f32_e32 v35, v34
	v_sub_f32_e32 v36, v34, v35
	v_fma_f32 v34, v58, s54, -v34
	v_fmac_f32_e32 v34, 0xb2a5705f, v58
	v_add_f32_e32 v34, v36, v34
	v_exp_f32_e32 v34, v34
	v_cvt_i32_f32_e32 v35, v35
	v_cmp_nlt_f32_e32 vcc, s55, v58
	v_pk_mul_f32 v[32:33], v[40:41], v[32:33]
	v_ldexp_f32 v34, v34, v35
	v_mul_f32_e32 v35, 0xbfb8aa3b, v59
	v_rndne_f32_e32 v36, v35
	v_sub_f32_e32 v37, v35, v36
	v_fma_f32 v35, v59, s54, -v35
	v_fmac_f32_e32 v35, 0xb2a5705f, v59
	v_add_f32_e32 v35, v37, v35
	v_exp_f32_e32 v35, v35
	v_cvt_i32_f32_e32 v36, v36
	v_cndmask_b32_e32 v34, 0, v34, vcc
	v_cmp_ngt_f32_e32 vcc, s56, v58
	v_cvt_pk_bf16_f32 v32, v32, v33
	v_ldexp_f32 v35, v35, v36
	v_cndmask_b32_e32 v34, v212, v34, vcc
	v_cmp_nlt_f32_e32 vcc, s55, v59
	s_nop 1
	v_cndmask_b32_e32 v35, 0, v35, vcc
	v_cmp_ngt_f32_e32 vcc, s56, v59
	s_nop 1
	v_cndmask_b32_e32 v35, v212, v35, vcc
	v_pk_add_f32 v[34:35], v[34:35], 1.0 op_sel_hi:[1,0]
	s_nop 0
	v_div_scale_f32 v36, s[10:11], v35, v35, v59
	v_rcp_f32_e32 v37, v36
	s_nop 0
	v_fma_f32 v38, -v36, v37, 1.0
	v_fmac_f32_e32 v37, v38, v37
	v_div_scale_f32 v38, vcc, v59, v35, v59
	v_mul_f32_e32 v39, v38, v37
	v_fma_f32 v40, -v36, v39, v38
	v_fmac_f32_e32 v39, v40, v37
	v_fma_f32 v36, -v36, v39, v38
	v_div_fmas_f32 v36, v36, v37, v39
	v_div_fixup_f32 v35, v36, v35, v59
	v_div_scale_f32 v36, s[10:11], v34, v34, v58
	v_rcp_f32_e32 v37, v36
	s_nop 0
	v_fma_f32 v38, -v36, v37, 1.0
	v_fmac_f32_e32 v37, v38, v37
	v_div_scale_f32 v38, vcc, v58, v34, v58
	v_mul_f32_e32 v39, v38, v37
	v_fma_f32 v40, -v36, v39, v38
	v_fmac_f32_e32 v39, v40, v37
	v_fma_f32 v36, -v36, v39, v38
	v_div_fmas_f32 v36, v36, v37, v39
	v_div_fixup_f32 v34, v36, v34, v58
	v_pk_mul_f32 v[34:35], v[42:43], v[34:35]
	v_cmp_nlt_f32_e32 vcc, s55, v60
	v_cvt_pk_bf16_f32 v33, v34, v35
	v_mul_f32_e32 v34, 0xbfb8aa3b, v60
	v_rndne_f32_e32 v35, v34
	v_sub_f32_e32 v36, v34, v35
	v_fma_f32 v34, v60, s54, -v34
; DEVI void lds_put4(char* wl, int RS, int row, int col, float a, float b, float c, float d) { u32x2 w = {cvtpk(a, b), cvtpk(c, d)}; *(u32x2*)(wl + row * RS + col * 2) = w; }
; DEVI float siluf(float x) { return x / (1.f + expf(-x)); }
; DEVI void phase_gemm_f1(const Params& p, int l, char* lds) {
;     ...
;     char* wl = lds + wid * (64 * 144);
; #pragma unroll
;     for (int cg2 = 0; cg2 < 2; ++cg2) {
; #pragma unroll
;       for (int mi = 0; mi < 2; ++mi) {
; #pragma unroll
;         for (int q = 0; q < 4; ++q) {
;           float h[4];
; #pragma unroll
;           for (int j = 0; j < 4; ++j) h[j] = siluf(acc[2 * cg2][mi][q * 4 + j]) * acc[2 * cg2 + 1][mi][q * 4 + j];
;           lds_put4(wl, 144, mi * 32 + r32, cg2 * 32 + q * 8 + hi * 4, h[0], h[1], h[2], h[3]);
;         }
	v_fmac_f32_e32 v34, 0xb2a5705f, v60
	v_add_f32_e32 v34, v36, v34
	v_exp_f32_e32 v34, v34
	v_cvt_i32_f32_e32 v35, v35
	v_ldexp_f32 v34, v34, v35
	v_mul_f32_e32 v35, 0xbfb8aa3b, v61
	v_rndne_f32_e32 v36, v35
	v_sub_f32_e32 v37, v35, v36
	v_fma_f32 v35, v61, s54, -v35
	v_fmac_f32_e32 v35, 0xb2a5705f, v61
	v_add_f32_e32 v35, v37, v35
	v_exp_f32_e32 v35, v35
	v_cvt_i32_f32_e32 v36, v36
	v_cndmask_b32_e32 v34, 0, v34, vcc
	v_cmp_ngt_f32_e32 vcc, s56, v60
	v_ldexp_f32 v35, v35, v36
	s_nop 0
	v_cndmask_b32_e32 v34, v212, v34, vcc
	v_cmp_nlt_f32_e32 vcc, s55, v61
	s_nop 1
	v_cndmask_b32_e32 v35, 0, v35, vcc
	v_cmp_ngt_f32_e32 vcc, s56, v61
	s_nop 1
	v_cndmask_b32_e32 v35, v212, v35, vcc
	v_pk_add_f32 v[34:35], v[34:35], 1.0 op_sel_hi:[1,0]
	s_nop 0
	v_div_scale_f32 v36, s[10:11], v35, v35, v61
	v_rcp_f32_e32 v37, v36
	s_nop 0
	v_fma_f32 v38, -v36, v37, 1.0
	v_fmac_f32_e32 v37, v38, v37
	v_div_scale_f32 v38, vcc, v61, v35, v61
	v_mul_f32_e32 v39, v38, v37
	v_fma_f32 v40, -v36, v39, v38
	v_fmac_f32_e32 v39, v40, v37
	v_fma_f32 v36, -v36, v39, v38
	v_div_fmas_f32 v36, v36, v37, v39
	v_div_fixup_f32 v35, v36, v35, v61
	v_div_scale_f32 v36, s[10:11], v34, v34, v60
	v_rcp_f32_e32 v37, v36
	s_nop 0
	v_fma_f32 v38, -v36, v37, 1.0
	v_fmac_f32_e32 v37, v38, v37
	v_div_scale_f32 v38, vcc, v60, v34, v60
	v_mul_f32_e32 v39, v38, v37
	v_fma_f32 v40, -v36, v39, v38
	v_fmac_f32_e32 v39, v40, v37
	v_fma_f32 v36, -v36, v39, v38
	v_div_fmas_f32 v36, v36, v37, v39
	v_div_fixup_f32 v34, v36, v34, v60
	v_mul_f32_e32 v36, 0xbfb8aa3b, v62
	v_rndne_f32_e32 v37, v36
	v_sub_f32_e32 v38, v36, v37
	v_fma_f32 v36, v62, s54, -v36
	v_fmac_f32_e32 v36, 0xb2a5705f, v62
	v_add_f32_e32 v36, v38, v36
	v_exp_f32_e32 v36, v36
	v_cvt_i32_f32_e32 v37, v37
	v_cmp_nlt_f32_e32 vcc, s55, v62
	v_pk_mul_f32 v[34:35], v[44:45], v[34:35]
	v_ldexp_f32 v36, v36, v37
	v_mul_f32_e32 v37, 0xbfb8aa3b, v63
	v_rndne_f32_e32 v38, v37
	v_sub_f32_e32 v39, v37, v38
	v_fma_f32 v37, v63, s54, -v37
	v_fmac_f32_e32 v37, 0xb2a5705f, v63
	v_add_f32_e32 v37, v39, v37
	v_exp_f32_e32 v37, v37
	v_cvt_i32_f32_e32 v38, v38
	v_cndmask_b32_e32 v36, 0, v36, vcc
	v_cmp_ngt_f32_e32 vcc, s56, v62
	v_cvt_pk_bf16_f32 v34, v34, v35
	v_ldexp_f32 v37, v37, v38
	v_cndmask_b32_e32 v36, v212, v36, vcc
	v_cmp_nlt_f32_e32 vcc, s55, v63
	s_nop 1
	v_cndmask_b32_e32 v37, 0, v37, vcc
	v_cmp_ngt_f32_e32 vcc, s56, v63
	s_nop 1
	v_cndmask_b32_e32 v37, v212, v37, vcc
	v_pk_add_f32 v[36:37], v[36:37], 1.0 op_sel_hi:[1,0]
	s_nop 0
	v_div_scale_f32 v38, s[10:11], v37, v37, v63
	v_rcp_f32_e32 v39, v38
	s_nop 0
	v_fma_f32 v40, -v38, v39, 1.0
	v_fmac_f32_e32 v39, v40, v39
	v_div_scale_f32 v40, vcc, v63, v37, v63
	v_mul_f32_e32 v41, v40, v39
	v_fma_f32 v42, -v38, v41, v40
	v_fmac_f32_e32 v41, v42, v39
	v_fma_f32 v38, -v38, v41, v40
	v_div_fmas_f32 v38, v38, v39, v41
	v_div_fixup_f32 v37, v38, v37, v63
	v_div_scale_f32 v38, s[10:11], v36, v36, v62
	v_rcp_f32_e32 v39, v38
	s_nop 0
	v_fma_f32 v40, -v38, v39, 1.0
	v_fmac_f32_e32 v39, v40, v39
	v_div_scale_f32 v40, vcc, v62, v36, v62
	v_mul_f32_e32 v41, v40, v39
	v_fma_f32 v42, -v38, v41, v40
	v_fmac_f32_e32 v41, v42, v39
	v_fma_f32 v38, -v38, v41, v40
	v_div_fmas_f32 v38, v38, v39, v41
	v_div_fixup_f32 v36, v38, v36, v62
	v_pk_mul_f32 v[36:37], v[46:47], v[36:37]
	v_cmp_nlt_f32_e32 vcc, s55, v16
	v_cvt_pk_bf16_f32 v35, v36, v37
	ds_write2_b64 v225, v[32:33], v[34:35] offset0:12 offset1:14
	v_mul_f32_e32 v32, 0xbfb8aa3b, v16
	v_rndne_f32_e32 v33, v32
	v_sub_f32_e32 v34, v32, v33
	v_fma_f32 v32, v16, s54, -v32
	v_fmac_f32_e32 v32, 0xb2a5705f, v16
	v_add_f32_e32 v32, v34, v32
	v_exp_f32_e32 v32, v32
	v_cvt_i32_f32_e32 v33, v33
	v_ldexp_f32 v32, v32, v33
	v_mul_f32_e32 v33, 0xbfb8aa3b, v17
	v_rndne_f32_e32 v34, v33
	v_sub_f32_e32 v35, v33, v34
	v_fma_f32 v33, v17, s54, -v33
	v_fmac_f32_e32 v33, 0xb2a5705f, v17
	v_add_f32_e32 v33, v35, v33
	v_exp_f32_e32 v33, v33
	v_cvt_i32_f32_e32 v34, v34
	v_cndmask_b32_e32 v32, 0, v32, vcc
	v_cmp_ngt_f32_e32 vcc, s56, v16
	v_ldexp_f32 v33, v33, v34
	s_nop 0
	v_cndmask_b32_e32 v32, v212, v32, vcc
	v_cmp_nlt_f32_e32 vcc, s55, v17
	s_nop 1
	v_cndmask_b32_e32 v33, 0, v33, vcc
	v_cmp_ngt_f32_e32 vcc, s56, v17
	s_nop 1
	v_cndmask_b32_e32 v33, v212, v33, vcc
	v_pk_add_f32 v[32:33], v[32:33], 1.0 op_sel_hi:[1,0]
	s_nop 0
	v_div_scale_f32 v34, s[10:11], v33, v33, v17
	v_rcp_f32_e32 v35, v34
	s_nop 0
	v_fma_f32 v36, -v34, v35, 1.0
	v_fmac_f32_e32 v35, v36, v35
	v_div_scale_f32 v36, vcc, v17, v33, v17
	v_mul_f32_e32 v37, v36, v35
	v_fma_f32 v38, -v34, v37, v36
	v_fmac_f32_e32 v37, v38, v35
	v_fma_f32 v34, -v34, v37, v36
	v_div_fmas_f32 v34, v34, v35, v37
	v_div_fixup_f32 v17, v34, v33, v17
	v_div_scale_f32 v33, s[10:11], v32, v32, v16
	v_rcp_f32_e32 v34, v33
	s_nop 0
	v_fma_f32 v35, -v33, v34, 1.0
	v_fmac_f32_e32 v34, v35, v34
	v_div_scale_f32 v35, vcc, v16, v32, v16
	v_mul_f32_e32 v36, v35, v34
	v_fma_f32 v37, -v33, v36, v35
	v_fmac_f32_e32 v36, v37, v34
	v_fma_f32 v33, -v33, v36, v35
	v_div_fmas_f32 v33, v33, v34, v36
	v_div_fixup_f32 v16, v33, v32, v16
	v_pk_mul_f32 v[0:1], v[0:1], v[16:17]
	v_mul_f32_e32 v16, 0xbfb8aa3b, v18
	v_rndne_f32_e32 v17, v16
	v_sub_f32_e32 v32, v16, v17
	v_fma_f32 v16, v18, s54, -v16
	v_fmac_f32_e32 v16, 0xb2a5705f, v18
	v_add_f32_e32 v16, v32, v16
	v_exp_f32_e32 v16, v16
	v_cvt_i32_f32_e32 v17, v17
	v_cmp_nlt_f32_e32 vcc, s55, v18
	v_cvt_pk_bf16_f32 v0, v0, v1
	v_ldexp_f32 v16, v16, v17
	v_mul_f32_e32 v17, 0xbfb8aa3b, v19
	v_rndne_f32_e32 v32, v17
	v_sub_f32_e32 v33, v17, v32
	v_fma_f32 v17, v19, s54, -v17
	v_fmac_f32_e32 v17, 0xb2a5705f, v19
	v_add_f32_e32 v17, v33, v17
	v_exp_f32_e32 v17, v17
	v_cvt_i32_f32_e32 v32, v32
	v_cndmask_b32_e32 v16, 0, v16, vcc
; DEVI void lds_put4(char* wl, int RS, int row, int col, float a, float b, float c, float d) { u32x2 w = {cvtpk(a, b), cvtpk(c, d)}; *(u32x2*)(wl + row * RS + col * 2) = w; }
; DEVI float siluf(float x) { return x / (1.f + expf(-x)); }
; DEVI void phase_gemm_f1(const Params& p, int l, char* lds) {
;     ...
;     char* wl = lds + wid * (64 * 144);
; #pragma unroll
;     for (int cg2 = 0; cg2 < 2; ++cg2) {
; #pragma unroll
;       for (int mi = 0; mi < 2; ++mi) {
; #pragma unroll
;         for (int q = 0; q < 4; ++q) {
;           float h[4];
; #pragma unroll
;           for (int j = 0; j < 4; ++j) h[j] = siluf(acc[2 * cg2][mi][q * 4 + j]) * acc[2 * cg2 + 1][mi][q * 4 + j];
;           lds_put4(wl, 144, mi * 32 + r32, cg2 * 32 + q * 8 + hi * 4, h[0], h[1], h[2], h[3]);
;         }
	v_cmp_ngt_f32_e32 vcc, s56, v18
	v_ldexp_f32 v17, v17, v32
	s_nop 0
	v_cndmask_b32_e32 v16, v212, v16, vcc
	v_cmp_nlt_f32_e32 vcc, s55, v19
	s_nop 1
	v_cndmask_b32_e32 v17, 0, v17, vcc
	v_cmp_ngt_f32_e32 vcc, s56, v19
	s_nop 1
	v_cndmask_b32_e32 v17, v212, v17, vcc
	v_pk_add_f32 v[16:17], v[16:17], 1.0 op_sel_hi:[1,0]
	s_nop 0
	v_div_scale_f32 v32, s[10:11], v17, v17, v19
	v_rcp_f32_e32 v33, v32
	s_nop 0
	v_fma_f32 v34, -v32, v33, 1.0
	v_fmac_f32_e32 v33, v34, v33
	v_div_scale_f32 v34, vcc, v19, v17, v19
	v_mul_f32_e32 v35, v34, v33
	v_fma_f32 v36, -v32, v35, v34
	v_fmac_f32_e32 v35, v36, v33
	v_fma_f32 v32, -v32, v35, v34
	v_div_fmas_f32 v32, v32, v33, v35
	v_div_fixup_f32 v17, v32, v17, v19
	v_div_scale_f32 v19, s[10:11], v16, v16, v18
	v_rcp_f32_e32 v32, v19
	s_nop 0
	v_fma_f32 v33, -v19, v32, 1.0
	v_fmac_f32_e32 v32, v33, v32
	v_div_scale_f32 v33, vcc, v18, v16, v18
	v_mul_f32_e32 v34, v33, v32
	v_fma_f32 v35, -v19, v34, v33
	v_fmac_f32_e32 v34, v35, v32
	v_fma_f32 v19, -v19, v34, v33
	v_div_fmas_f32 v19, v19, v32, v34
	v_div_fixup_f32 v16, v19, v16, v18
	v_pk_mul_f32 v[2:3], v[2:3], v[16:17]
	v_cmp_nlt_f32_e32 vcc, s55, v20
	v_cvt_pk_bf16_f32 v1, v2, v3
	v_mul_f32_e32 v2, 0xbfb8aa3b, v20
	v_rndne_f32_e32 v3, v2
	v_sub_f32_e32 v16, v2, v3
	v_fma_f32 v2, v20, s54, -v2
	v_fmac_f32_e32 v2, 0xb2a5705f, v20
	v_add_f32_e32 v2, v16, v2
	v_exp_f32_e32 v2, v2
	v_cvt_i32_f32_e32 v3, v3
	v_ldexp_f32 v2, v2, v3
	v_mul_f32_e32 v3, 0xbfb8aa3b, v21
	v_rndne_f32_e32 v16, v3
	v_sub_f32_e32 v17, v3, v16
	v_fma_f32 v3, v21, s54, -v3
	v_fmac_f32_e32 v3, 0xb2a5705f, v21
	v_add_f32_e32 v3, v17, v3
	v_exp_f32_e32 v3, v3
	v_cvt_i32_f32_e32 v16, v16
	v_cndmask_b32_e32 v2, 0, v2, vcc
	v_cmp_ngt_f32_e32 vcc, s56, v20
	v_ldexp_f32 v3, v3, v16
	s_nop 0
	v_cndmask_b32_e32 v2, v212, v2, vcc
	v_cmp_nlt_f32_e32 vcc, s55, v21
	s_nop 1
	v_cndmask_b32_e32 v3, 0, v3, vcc
	v_cmp_ngt_f32_e32 vcc, s56, v21
	s_nop 1
	v_cndmask_b32_e32 v3, v212, v3, vcc
	v_pk_add_f32 v[2:3], v[2:3], 1.0 op_sel_hi:[1,0]
	s_nop 0
	v_div_scale_f32 v16, s[10:11], v3, v3, v21
	v_rcp_f32_e32 v17, v16
	s_nop 0
	v_fma_f32 v18, -v16, v17, 1.0
	v_fmac_f32_e32 v17, v18, v17
	v_div_scale_f32 v18, vcc, v21, v3, v21
	v_mul_f32_e32 v19, v18, v17
	v_fma_f32 v32, -v16, v19, v18
	v_fmac_f32_e32 v19, v32, v17
	v_fma_f32 v16, -v16, v19, v18
	v_div_fmas_f32 v16, v16, v17, v19
	v_div_fixup_f32 v3, v16, v3, v21
	v_div_scale_f32 v16, s[10:11], v2, v2, v20
	v_rcp_f32_e32 v17, v16
	s_nop 0
	v_fma_f32 v18, -v16, v17, 1.0
	v_fmac_f32_e32 v17, v18, v17
	v_div_scale_f32 v18, vcc, v20, v2, v20
	v_mul_f32_e32 v19, v18, v17
	v_fma_f32 v21, -v16, v19, v18
	v_fmac_f32_e32 v19, v21, v17
	v_fma_f32 v16, -v16, v19, v18
	v_div_fmas_f32 v16, v16, v17, v19
	v_div_fixup_f32 v2, v16, v2, v20
	v_pk_mul_f32 v[2:3], v[4:5], v[2:3]
	v_mul_f32_e32 v4, 0xbfb8aa3b, v22
	v_rndne_f32_e32 v5, v4
	v_sub_f32_e32 v16, v4, v5
	v_fma_f32 v4, v22, s54, -v4
	v_fmac_f32_e32 v4, 0xb2a5705f, v22
	v_add_f32_e32 v4, v16, v4
	v_exp_f32_e32 v4, v4
	v_cvt_i32_f32_e32 v5, v5
	v_cmp_nlt_f32_e32 vcc, s55, v22
	v_cvt_pk_bf16_f32 v2, v2, v3
	v_ldexp_f32 v4, v4, v5
	v_mul_f32_e32 v5, 0xbfb8aa3b, v23
	v_rndne_f32_e32 v16, v5
	v_sub_f32_e32 v17, v5, v16
	v_fma_f32 v5, v23, s54, -v5
	v_fmac_f32_e32 v5, 0xb2a5705f, v23
	v_add_f32_e32 v5, v17, v5
	v_exp_f32_e32 v5, v5
	v_cvt_i32_f32_e32 v16, v16
	v_cndmask_b32_e32 v4, 0, v4, vcc
	v_cmp_ngt_f32_e32 vcc, s56, v22
	v_ldexp_f32 v5, v5, v16
	s_nop 0
	v_cndmask_b32_e32 v4, v212, v4, vcc
	v_cmp_nlt_f32_e32 vcc, s55, v23
	s_nop 1
	v_cndmask_b32_e32 v5, 0, v5, vcc
	v_cmp_ngt_f32_e32 vcc, s56, v23
	s_nop 1
	v_cndmask_b32_e32 v5, v212, v5, vcc
	v_pk_add_f32 v[4:5], v[4:5], 1.0 op_sel_hi:[1,0]
	s_nop 0
	v_div_scale_f32 v16, s[10:11], v5, v5, v23
	v_rcp_f32_e32 v17, v16
	s_nop 0
	v_fma_f32 v18, -v16, v17, 1.0
	v_fmac_f32_e32 v17, v18, v17
	v_div_scale_f32 v18, vcc, v23, v5, v23
	v_mul_f32_e32 v19, v18, v17
	v_fma_f32 v20, -v16, v19, v18
	v_fmac_f32_e32 v19, v20, v17
	v_fma_f32 v16, -v16, v19, v18
	v_div_fmas_f32 v16, v16, v17, v19
	v_div_fixup_f32 v5, v16, v5, v23
	v_div_scale_f32 v16, s[10:11], v4, v4, v22
	v_rcp_f32_e32 v17, v16
	s_nop 0
	v_fma_f32 v18, -v16, v17, 1.0
	v_fmac_f32_e32 v17, v18, v17
	v_div_scale_f32 v18, vcc, v22, v4, v22
	v_mul_f32_e32 v19, v18, v17
	v_fma_f32 v20, -v16, v19, v18
	v_fmac_f32_e32 v19, v20, v17
	v_fma_f32 v16, -v16, v19, v18
	v_div_fmas_f32 v16, v16, v17, v19
	v_div_fixup_f32 v4, v16, v4, v22
	v_pk_mul_f32 v[4:5], v[6:7], v[4:5]
	v_cmp_nlt_f32_e32 vcc, s55, v24
	v_cvt_pk_bf16_f32 v3, v4, v5
	ds_write2_b64 v66, v[0:1], v[2:3] offset0:72 offset1:74
	v_mul_f32_e32 v0, 0xbfb8aa3b, v24
	v_rndne_f32_e32 v1, v0
	v_sub_f32_e32 v2, v0, v1
	v_fma_f32 v0, v24, s54, -v0
	v_fmac_f32_e32 v0, 0xb2a5705f, v24
	v_add_f32_e32 v0, v2, v0
	v_exp_f32_e32 v0, v0
	v_cvt_i32_f32_e32 v1, v1
	v_ldexp_f32 v0, v0, v1
	v_mul_f32_e32 v1, 0xbfb8aa3b, v25
	v_rndne_f32_e32 v2, v1
	v_sub_f32_e32 v3, v1, v2
	v_fma_f32 v1, v25, s54, -v1
	v_fmac_f32_e32 v1, 0xb2a5705f, v25
	v_add_f32_e32 v1, v3, v1
	v_exp_f32_e32 v1, v1
	v_cvt_i32_f32_e32 v2, v2
	v_cndmask_b32_e32 v0, 0, v0, vcc
	v_cmp_ngt_f32_e32 vcc, s56, v24
	v_ldexp_f32 v1, v1, v2
	s_nop 0
	v_cndmask_b32_e32 v0, v212, v0, vcc
	v_cmp_nlt_f32_e32 vcc, s55, v25
	s_nop 1
	v_cndmask_b32_e32 v1, 0, v1, vcc
	v_cmp_ngt_f32_e32 vcc, s56, v25
	s_nop 1
	v_cndmask_b32_e32 v1, v212, v1, vcc
	v_pk_add_f32 v[0:1], v[0:1], 1.0 op_sel_hi:[1,0]
	s_nop 0
	v_div_scale_f32 v2, s[10:11], v1, v1, v25
	v_rcp_f32_e32 v3, v2
	s_nop 0
	v_fma_f32 v4, -v2, v3, 1.0
	v_fmac_f32_e32 v3, v4, v3
	v_div_scale_f32 v4, vcc, v25, v1, v25
	v_mul_f32_e32 v5, v4, v3
	v_fma_f32 v6, -v2, v5, v4
	v_fmac_f32_e32 v5, v6, v3
; DEVI void lds_put4(char* wl, int RS, int row, int col, float a, float b, float c, float d) { u32x2 w = {cvtpk(a, b), cvtpk(c, d)}; *(u32x2*)(wl + row * RS + col * 2) = w; }
; DEVI float siluf(float x) { return x / (1.f + expf(-x)); }
; DEVI void phase_gemm_f1(const Params& p, int l, char* lds) {
;     ...
;     for (int cg2 = 0; cg2 < 2; ++cg2) {
; #pragma unroll
;       for (int mi = 0; mi < 2; ++mi) {
; #pragma unroll
;         for (int q = 0; q < 4; ++q) {
;           float h[4];
; #pragma unroll
;           for (int j = 0; j < 4; ++j) h[j] = siluf(acc[2 * cg2][mi][q * 4 + j]) * acc[2 * cg2 + 1][mi][q * 4 + j];
;           lds_put4(wl, 144, mi * 32 + r32, cg2 * 32 + q * 8 + hi * 4, h[0], h[1], h[2], h[3]);
;         }
;       }
;     }
;     wave_tile_store<64>(wl, hid + (long)(m0 + wm * 64) * FH + (tn * 4 + wn * 2) * 32, FH, lane);
	v_fma_f32 v2, -v2, v5, v4
	v_div_fmas_f32 v2, v2, v3, v5
	v_div_fixup_f32 v1, v2, v1, v25
	v_div_scale_f32 v2, s[10:11], v0, v0, v24
	v_rcp_f32_e32 v3, v2
	s_nop 0
	v_fma_f32 v4, -v2, v3, 1.0
	v_fmac_f32_e32 v3, v4, v3
	v_div_scale_f32 v4, vcc, v24, v0, v24
	v_mul_f32_e32 v5, v4, v3
	v_fma_f32 v6, -v2, v5, v4
	v_fmac_f32_e32 v5, v6, v3
	v_fma_f32 v2, -v2, v5, v4
	v_div_fmas_f32 v2, v2, v3, v5
	v_div_fixup_f32 v0, v2, v0, v24
	v_mul_f32_e32 v2, 0xbfb8aa3b, v26
	v_rndne_f32_e32 v3, v2
	v_sub_f32_e32 v4, v2, v3
	v_fma_f32 v2, v26, s54, -v2
	v_fmac_f32_e32 v2, 0xb2a5705f, v26
	v_add_f32_e32 v2, v4, v2
	v_exp_f32_e32 v2, v2
	v_cvt_i32_f32_e32 v3, v3
	v_cmp_nlt_f32_e32 vcc, s55, v26
	v_pk_mul_f32 v[0:1], v[8:9], v[0:1]
	v_ldexp_f32 v2, v2, v3
	v_mul_f32_e32 v3, 0xbfb8aa3b, v27
	v_rndne_f32_e32 v4, v3
	v_sub_f32_e32 v5, v3, v4
	v_fma_f32 v3, v27, s54, -v3
	v_fmac_f32_e32 v3, 0xb2a5705f, v27
	v_add_f32_e32 v3, v5, v3
	v_exp_f32_e32 v3, v3
	v_cvt_i32_f32_e32 v4, v4
	v_cndmask_b32_e32 v2, 0, v2, vcc
	v_cmp_ngt_f32_e32 vcc, s56, v26
	v_cvt_pk_bf16_f32 v0, v0, v1
	v_ldexp_f32 v3, v3, v4
	v_cndmask_b32_e32 v2, v212, v2, vcc
	v_cmp_nlt_f32_e32 vcc, s55, v27
	s_nop 1
	v_cndmask_b32_e32 v3, 0, v3, vcc
	v_cmp_ngt_f32_e32 vcc, s56, v27
	s_nop 1
	v_cndmask_b32_e32 v3, v212, v3, vcc
	v_pk_add_f32 v[2:3], v[2:3], 1.0 op_sel_hi:[1,0]
	s_nop 0
	v_div_scale_f32 v4, s[10:11], v3, v3, v27
	v_rcp_f32_e32 v5, v4
	s_nop 0
	v_fma_f32 v6, -v4, v5, 1.0
	v_fmac_f32_e32 v5, v6, v5
	v_div_scale_f32 v6, vcc, v27, v3, v27
	v_mul_f32_e32 v7, v6, v5
	v_fma_f32 v8, -v4, v7, v6
	v_fmac_f32_e32 v7, v8, v5
	v_fma_f32 v4, -v4, v7, v6
	v_div_fmas_f32 v4, v4, v5, v7
	v_div_fixup_f32 v3, v4, v3, v27
	v_div_scale_f32 v4, s[10:11], v2, v2, v26
	v_rcp_f32_e32 v5, v4
	s_nop 0
	v_fma_f32 v6, -v4, v5, 1.0
	v_fmac_f32_e32 v5, v6, v5
	v_div_scale_f32 v6, vcc, v26, v2, v26
	v_mul_f32_e32 v7, v6, v5
	v_fma_f32 v8, -v4, v7, v6
	v_fmac_f32_e32 v7, v8, v5
	v_fma_f32 v4, -v4, v7, v6
	v_div_fmas_f32 v4, v4, v5, v7
	v_div_fixup_f32 v2, v4, v2, v26
	v_pk_mul_f32 v[2:3], v[10:11], v[2:3]
	v_cmp_nlt_f32_e32 vcc, s55, v28
	v_cvt_pk_bf16_f32 v1, v2, v3
	v_mul_f32_e32 v2, 0xbfb8aa3b, v28
	v_rndne_f32_e32 v3, v2
	v_sub_f32_e32 v4, v2, v3
	v_fma_f32 v2, v28, s54, -v2
	v_fmac_f32_e32 v2, 0xb2a5705f, v28
	v_add_f32_e32 v2, v4, v2
	v_exp_f32_e32 v2, v2
	v_cvt_i32_f32_e32 v3, v3
	v_ldexp_f32 v2, v2, v3
	v_mul_f32_e32 v3, 0xbfb8aa3b, v29
	v_rndne_f32_e32 v4, v3
	v_sub_f32_e32 v5, v3, v4
	v_fma_f32 v3, v29, s54, -v3
	v_fmac_f32_e32 v3, 0xb2a5705f, v29
	v_add_f32_e32 v3, v5, v3
	v_exp_f32_e32 v3, v3
	v_cvt_i32_f32_e32 v4, v4
	v_cndmask_b32_e32 v2, 0, v2, vcc
	v_cmp_ngt_f32_e32 vcc, s56, v28
	v_ldexp_f32 v3, v3, v4
	s_nop 0
	v_cndmask_b32_e32 v2, v212, v2, vcc
	v_cmp_nlt_f32_e32 vcc, s55, v29
	s_nop 1
	v_cndmask_b32_e32 v3, 0, v3, vcc
	v_cmp_ngt_f32_e32 vcc, s56, v29
	s_nop 1
	v_cndmask_b32_e32 v3, v212, v3, vcc
	v_pk_add_f32 v[2:3], v[2:3], 1.0 op_sel_hi:[1,0]
	s_nop 0
	v_div_scale_f32 v4, s[10:11], v3, v3, v29
	v_rcp_f32_e32 v5, v4
	s_nop 0
	v_fma_f32 v6, -v4, v5, 1.0
	v_fmac_f32_e32 v5, v6, v5
	v_div_scale_f32 v6, vcc, v29, v3, v29
	v_mul_f32_e32 v7, v6, v5
	v_fma_f32 v8, -v4, v7, v6
	v_fmac_f32_e32 v7, v8, v5
	v_fma_f32 v4, -v4, v7, v6
	v_div_fmas_f32 v4, v4, v5, v7
	v_div_fixup_f32 v3, v4, v3, v29
	v_div_scale_f32 v4, s[10:11], v2, v2, v28
	v_rcp_f32_e32 v5, v4
	s_nop 0
	v_fma_f32 v6, -v4, v5, 1.0
	v_fmac_f32_e32 v5, v6, v5
	v_div_scale_f32 v6, vcc, v28, v2, v28
	v_mul_f32_e32 v7, v6, v5
	v_fma_f32 v8, -v4, v7, v6
	v_fmac_f32_e32 v7, v8, v5
	v_fma_f32 v4, -v4, v7, v6
	v_div_fmas_f32 v4, v4, v5, v7
	v_div_fixup_f32 v2, v4, v2, v28
	v_mul_f32_e32 v4, 0xbfb8aa3b, v30
	v_rndne_f32_e32 v5, v4
	v_sub_f32_e32 v6, v4, v5
	v_fma_f32 v4, v30, s54, -v4
	v_fmac_f32_e32 v4, 0xb2a5705f, v30
	v_add_f32_e32 v4, v6, v4
	v_exp_f32_e32 v4, v4
	v_cvt_i32_f32_e32 v5, v5
	v_cmp_nlt_f32_e32 vcc, s55, v30
	v_pk_mul_f32 v[2:3], v[12:13], v[2:3]
	v_ldexp_f32 v4, v4, v5
	v_mul_f32_e32 v5, 0xbfb8aa3b, v31
	v_rndne_f32_e32 v6, v5
	v_sub_f32_e32 v7, v5, v6
	v_fma_f32 v5, v31, s54, -v5
	v_fmac_f32_e32 v5, 0xb2a5705f, v31
	v_add_f32_e32 v5, v7, v5
	v_exp_f32_e32 v5, v5
	v_cvt_i32_f32_e32 v6, v6
	v_cndmask_b32_e32 v4, 0, v4, vcc
	v_cmp_ngt_f32_e32 vcc, s56, v30
	v_cvt_pk_bf16_f32 v2, v2, v3
	v_ldexp_f32 v5, v5, v6
	v_cndmask_b32_e32 v4, v212, v4, vcc
	v_cmp_nlt_f32_e32 vcc, s55, v31
	s_nop 1
	v_cndmask_b32_e32 v5, 0, v5, vcc
	v_cmp_ngt_f32_e32 vcc, s56, v31
	s_nop 1
	v_cndmask_b32_e32 v5, v212, v5, vcc
	v_pk_add_f32 v[4:5], v[4:5], 1.0 op_sel_hi:[1,0]
	s_nop 0
	v_div_scale_f32 v6, s[10:11], v5, v5, v31
	v_rcp_f32_e32 v7, v6
	s_nop 0
	v_fma_f32 v8, -v6, v7, 1.0
	v_fmac_f32_e32 v7, v8, v7
	v_div_scale_f32 v8, vcc, v31, v5, v31
	v_mul_f32_e32 v9, v8, v7
	v_fma_f32 v10, -v6, v9, v8
	v_fmac_f32_e32 v9, v10, v7
	v_fma_f32 v6, -v6, v9, v8
	v_div_fmas_f32 v6, v6, v7, v9
	v_div_fixup_f32 v5, v6, v5, v31
	v_div_scale_f32 v6, s[10:11], v4, v4, v30
	v_rcp_f32_e32 v7, v6
	s_nop 0
	v_fma_f32 v8, -v6, v7, 1.0
	v_fmac_f32_e32 v7, v8, v7
	v_div_scale_f32 v8, vcc, v30, v4, v30
	v_mul_f32_e32 v9, v8, v7
	v_fma_f32 v10, -v6, v9, v8
	v_fmac_f32_e32 v9, v10, v7
	v_fma_f32 v6, -v6, v9, v8
	v_div_fmas_f32 v6, v6, v7, v9
	v_div_fixup_f32 v4, v6, v4, v30
	v_pk_mul_f32 v[4:5], v[14:15], v[4:5]
	s_nop 0
	v_cvt_pk_bf16_f32 v3, v4, v5
	ds_write2_b64 v66, v[0:1], v[2:3] offset0:76 offset1:78
	v_or_b32_e32 v2, s8, v222
	v_lshl_add_u32 v0, s9, 7, v223
	v_ashrrev_i32_e32 v1, 31, v0
	v_lshlrev_b64 v[0:1], 1, v[0:1]
	s_movk_i32 s8, 0x1600
	v_mad_i64_i32 v[0:1], s[8:9], v2, s8, v[0:1]
	v_lshl_add_u64 v[0:1], v[194:195], 0, v[0:1]
	s_mov_b64 s[8:9], 0
	v_mov_b32_e32 v2, v224
